# U sweep: first four dot products as v_dot2_f32_bf16 with zero addend (no accumulator clears); V sweep: pads behind f32 converts removed
# baseline (speedup 1.0000x reference)
; __device__ __forceinline__ float dot2pb(__bf16 x0, __bf16 x1, unsigned h, float c) { bf2_t x; x[0] = x0; x[1] = x1; bf2_t y; __builtin_memcpy(&y, &h, 4); return __builtin_amdgcn_fdot2_f32_bf16(x, y, c, false); }
; __device__ void ph_peer(const float* __restrict__ SC, const bf16_t* __restrict__ H  , const float* __restrict__ gffn, const unsigned char* __restrict__ U, const unsigned char* __restrict__ V, float* X, const float* __restrict__ fgain) {
;     ...
;         for (int it = 0; it < 32; ++it) {
;             const int src = (it * 4 + grp) & 63;
;             const int e = __shfl(it < 16 ? idx_lo : idx_hi, src);
;             const float gt = __shfl(it < 16 ? g_lo : g_hi, src);
;             const u32x4* up = (const u32x4*)(U + (size_t)e * 768 + 48 * sub);
;             const u32x4 u0 = up[0], u1 = up[1], u2 = up[2];
;             u32x2 vw[2][3];
; #pragma unroll
;             for (int r = 0; r < 2; ++r) { const int ea = __builtin_amdgcn_readlane(e, 32 * r), eb = __builtin_amdgcn_readlane(e, 32 * r + 16);
;                 const u32x2* vp = (const u32x2*)(V + (size_t)(half ? eb : ea) * 768 + 24 * c32); vw[r][0] = vp[0]; vw[r][1] = vp[1]; vw[r][2] = vp[2]; }
;             float d0 = 0.f, d1 = 0.f, d2 = 0.f, d3 = 0.f;
;             {   const v6u_t p0 = (v6u_t){u0.x, u0.y, u0.z, u0.w, u1.x, u1.y};
;                 const v32bf_t r0 = __builtin_amdgcn_cvt_scalef32_pk32_bf16_fp6(p0, 1.0f);
; #pragma unroll
;                 for (int k = 0; k < 16; k += 4) { d0 = dot2pb(r0[2 * k], r0[2 * k + 1], hf2[k], d0); d1 = dot2pb(r0[2 * k + 2], r0[2 * k + 3], hf2[k + 1], d1);
;                     d2 = dot2pb(r0[2 * k + 4], r0[2 * k + 5], hf2[k + 2], d2); d3 = dot2pb(r0[2 * k + 6], r0[2 * k + 7], hf2[k + 3], d3); } }
;             {   const v6u_t p1 = (v6u_t){u1.z, u1.w, u2.x, u2.y, u2.z, u2.w};
;                 const v32bf_t r1 = __builtin_amdgcn_cvt_scalef32_pk32_bf16_fp6(p1, 1.0f);
; #pragma unroll
;                 for (int k = 0; k < 16; k += 4) { d0 = dot2pb(r1[2 * k], r1[2 * k + 1], hf2[16 + k], d0); d1 = dot2pb(r1[2 * k + 2], r1[2 * k + 3], hf2[16 + k + 1], d1);
;                     d2 = dot2pb(r1[2 * k + 4], r1[2 * k + 5], hf2[16 + k + 2], d2); d3 = dot2pb(r1[2 * k + 6], r1[2 * k + 7], hf2[16 + k + 3], d3); } }
;             const float d = row16_sum((d0 + d1) + (d2 + d3)) * FP6_INV;
.Lpeer_uloop:
	ds_read_b32 v58, v61 offset:1520
	ds_read_b32 v59, v61 offset:2032
	s_waitcnt lgkmcnt(1)
	v_mad_u32_u24 v0, v58, s14, v92
	global_load_dwordx4 v[44:47], v0, s[46:47]
	global_load_dwordx4 v[48:51], v0, s[46:47] offset:16
	global_load_dwordx4 v[52:55], v0, s[46:47] offset:32
	s_waitcnt vmcnt(4)
	v_cvt_scalef32_pk32_bf16_fp6 v[0:15], v[32:37], 1.0
	v_dot2_f32_bf16 v23, v0, v95, 0
	v_dot2_f32_bf16 v25, v1, v159, 0
	v_dot2_f32_bf16 v22, v2, v160, 0
	v_dot2_f32_bf16 v24, v3, v161, 0
	v_dot2c_f32_bf16_e32 v23, v4, v180
	v_dot2c_f32_bf16_e32 v25, v5, v181
	v_dot2c_f32_bf16_e32 v22, v6, v182
	v_dot2c_f32_bf16_e32 v24, v7, v183
	v_dot2c_f32_bf16_e32 v23, v8, v184
	v_dot2c_f32_bf16_e32 v25, v9, v185
	v_dot2c_f32_bf16_e32 v22, v10, v186
	v_dot2c_f32_bf16_e32 v24, v11, v187
	v_dot2c_f32_bf16_e32 v23, v12, v188
	v_dot2c_f32_bf16_e32 v25, v13, v189
	v_dot2c_f32_bf16_e32 v22, v14, v190
	v_dot2c_f32_bf16_e32 v24, v15, v191
	s_waitcnt vmcnt(3)
	v_cvt_scalef32_pk32_bf16_fp6 v[0:15], v[38:43], 1.0
	v_dot2c_f32_bf16_e32 v23, v0, v192
	v_dot2c_f32_bf16_e32 v25, v1, v193
	v_dot2c_f32_bf16_e32 v22, v2, v194
	v_dot2c_f32_bf16_e32 v24, v3, v195
	v_dot2c_f32_bf16_e32 v23, v4, v196
	v_dot2c_f32_bf16_e32 v25, v5, v197
	v_dot2c_f32_bf16_e32 v22, v6, v198
	v_dot2c_f32_bf16_e32 v24, v7, v199
	v_dot2c_f32_bf16_e32 v23, v8, v200
	v_dot2c_f32_bf16_e32 v25, v9, v201
	v_dot2c_f32_bf16_e32 v22, v10, v202
	v_dot2c_f32_bf16_e32 v24, v11, v203
	v_dot2c_f32_bf16_e32 v23, v12, v204
	v_dot2c_f32_bf16_e32 v25, v13, v205
	v_dot2c_f32_bf16_e32 v22, v14, v206
	v_dot2c_f32_bf16_e32 v24, v15, v207
	s_nop 2
	v_pk_add_f32 v[0:1], v[24:25], v[22:23]
	s_nop 0
	v_add_f32_e32 v0, v0, v1
	s_nop 1
	v_add_f32_dpp v0, v0, v0 quad_perm:[1,0,3,2] row_mask:0xf bank_mask:0xf bound_ctrl:1
	s_nop 1
	v_add_f32_dpp v0, v0, v0 quad_perm:[2,3,0,1] row_mask:0xf bank_mask:0xf bound_ctrl:1
	s_nop 1
	v_add_f32_dpp v0, v0, v0 row_half_mirror row_mask:0xf bank_mask:0xf bound_ctrl:1
	s_nop 1
	v_add_f32_dpp v0, v0, v0 row_mirror row_mask:0xf bank_mask:0xf bound_ctrl:1
	s_waitcnt lgkmcnt(0)
	v_cndmask_b32_e64 v208, v208, v0, s[50:51]
	v_cndmask_b32_e64 v209, v209, v57, s[50:51]
	ds_read_b32 v56, v61
	ds_read_b32 v57, v61 offset:512
	v_add_u32_e32 v61, 16, v61
	s_add_i32 s1, s1, 1
	s_waitcnt lgkmcnt(1)
	v_mad_u32_u24 v0, v56, s14, v92
	global_load_dwordx4 v[32:35], v0, s[46:47]
	global_load_dwordx4 v[36:39], v0, s[46:47] offset:16
	global_load_dwordx4 v[40:43], v0, s[46:47] offset:32
	s_waitcnt vmcnt(4)
	v_cvt_scalef32_pk32_bf16_fp6 v[0:15], v[44:49], 1.0
	v_dot2_f32_bf16 v23, v0, v212, 0
	v_dot2_f32_bf16 v25, v1, v213, 0
	v_dot2_f32_bf16 v22, v2, v214, 0
	v_dot2_f32_bf16 v24, v3, v215, 0
	v_dot2c_f32_bf16_e32 v23, v4, v218
	v_dot2c_f32_bf16_e32 v25, v5, v219
	v_dot2c_f32_bf16_e32 v22, v6, v220
	v_dot2c_f32_bf16_e32 v24, v7, v221
	v_dot2c_f32_bf16_e32 v23, v8, v222
	v_dot2c_f32_bf16_e32 v25, v9, v223
	v_dot2c_f32_bf16_e32 v22, v10, v224
	v_dot2c_f32_bf16_e32 v24, v11, v225
	v_dot2c_f32_bf16_e32 v23, v12, v226
	v_dot2c_f32_bf16_e32 v25, v13, v227
	v_dot2c_f32_bf16_e32 v22, v14, v228
	v_dot2c_f32_bf16_e32 v24, v15, v229
	s_waitcnt vmcnt(3)
	v_cvt_scalef32_pk32_bf16_fp6 v[0:15], v[50:55], 1.0
	v_dot2c_f32_bf16_e32 v23, v0, v230
	v_dot2c_f32_bf16_e32 v25, v1, v231
	v_dot2c_f32_bf16_e32 v22, v2, v232
	v_dot2c_f32_bf16_e32 v24, v3, v233
	v_dot2c_f32_bf16_e32 v23, v4, v234
	v_dot2c_f32_bf16_e32 v25, v5, v235
	v_dot2c_f32_bf16_e32 v22, v6, v236
	v_dot2c_f32_bf16_e32 v24, v7, v237
	v_dot2c_f32_bf16_e32 v23, v8, v238
	v_dot2c_f32_bf16_e32 v25, v9, v239
	v_dot2c_f32_bf16_e32 v22, v10, v240
	v_dot2c_f32_bf16_e32 v24, v11, v241
	v_dot2c_f32_bf16_e32 v23, v12, v242
	v_dot2c_f32_bf16_e32 v25, v13, v243
	v_dot2c_f32_bf16_e32 v22, v14, v244
	v_dot2c_f32_bf16_e32 v24, v15, v245
	s_nop 2
	v_pk_add_f32 v[0:1], v[24:25], v[22:23]
	s_nop 0
	v_add_f32_e32 v0, v0, v1
	s_nop 1
	v_add_f32_dpp v0, v0, v0 quad_perm:[1,0,3,2] row_mask:0xf bank_mask:0xf bound_ctrl:1
	s_nop 1
	v_add_f32_dpp v0, v0, v0 quad_perm:[2,3,0,1] row_mask:0xf bank_mask:0xf bound_ctrl:1
	s_nop 1
	v_add_f32_dpp v0, v0, v0 row_half_mirror row_mask:0xf bank_mask:0xf bound_ctrl:1
	s_nop 1
	v_add_f32_dpp v0, v0, v0 row_mirror row_mask:0xf bank_mask:0xf bound_ctrl:1
	s_waitcnt lgkmcnt(0)
	v_cndmask_b32_e64 v210, v210, v0, s[50:51]
	v_cndmask_b32_e64 v211, v211, v59, s[50:51]
	ds_read_b32 v58, v61 offset:1520
	ds_read_b32 v59, v61 offset:2032
	s_waitcnt lgkmcnt(1)
	v_mad_u32_u24 v0, v58, s14, v92
	global_load_dwordx4 v[44:47], v0, s[46:47]
	global_load_dwordx4 v[48:51], v0, s[46:47] offset:16
	global_load_dwordx4 v[52:55], v0, s[46:47] offset:32
	s_waitcnt vmcnt(4)
	v_cvt_scalef32_pk32_bf16_fp6 v[0:15], v[32:37], 1.0
	v_dot2_f32_bf16 v23, v0, v95, 0
	v_dot2_f32_bf16 v25, v1, v159, 0
	v_dot2_f32_bf16 v22, v2, v160, 0
	v_dot2_f32_bf16 v24, v3, v161, 0
	v_dot2c_f32_bf16_e32 v23, v4, v180
	v_dot2c_f32_bf16_e32 v25, v5, v181
	v_dot2c_f32_bf16_e32 v22, v6, v182
	v_dot2c_f32_bf16_e32 v24, v7, v183
	v_dot2c_f32_bf16_e32 v23, v8, v184
	v_dot2c_f32_bf16_e32 v25, v9, v185
	v_dot2c_f32_bf16_e32 v22, v10, v186
	v_dot2c_f32_bf16_e32 v24, v11, v187
	v_dot2c_f32_bf16_e32 v23, v12, v188
	v_dot2c_f32_bf16_e32 v25, v13, v189
	v_dot2c_f32_bf16_e32 v22, v14, v190
	v_dot2c_f32_bf16_e32 v24, v15, v191
	s_waitcnt vmcnt(3)
; __device__ __forceinline__ float dot2pb(__bf16 x0, __bf16 x1, unsigned h, float c) { bf2_t x; x[0] = x0; x[1] = x1; bf2_t y; __builtin_memcpy(&y, &h, 4); return __builtin_amdgcn_fdot2_f32_bf16(x, y, c, false); }
; __device__ void ph_peer(const float* __restrict__ SC, const bf16_t* __restrict__ H  , const float* __restrict__ gffn, const unsigned char* __restrict__ U, const unsigned char* __restrict__ V, float* X, const float* __restrict__ fgain) {
;     ...
;         for (int it = 0; it < 32; ++it) {
;             const int src = (it * 4 + grp) & 63;
;             const int e = __shfl(it < 16 ? idx_lo : idx_hi, src);
;             const float gt = __shfl(it < 16 ? g_lo : g_hi, src);
;             const u32x4* up = (const u32x4*)(U + (size_t)e * 768 + 48 * sub);
;             const u32x4 u0 = up[0], u1 = up[1], u2 = up[2];
;             u32x2 vw[2][3];
; #pragma unroll
;             for (int r = 0; r < 2; ++r) { const int ea = __builtin_amdgcn_readlane(e, 32 * r), eb = __builtin_amdgcn_readlane(e, 32 * r + 16);
;                 const u32x2* vp = (const u32x2*)(V + (size_t)(half ? eb : ea) * 768 + 24 * c32); vw[r][0] = vp[0]; vw[r][1] = vp[1]; vw[r][2] = vp[2]; }
;             float d0 = 0.f, d1 = 0.f, d2 = 0.f, d3 = 0.f;
;             {   const v6u_t p0 = (v6u_t){u0.x, u0.y, u0.z, u0.w, u1.x, u1.y};
;                 const v32bf_t r0 = __builtin_amdgcn_cvt_scalef32_pk32_bf16_fp6(p0, 1.0f);
; #pragma unroll
;                 for (int k = 0; k < 16; k += 4) { d0 = dot2pb(r0[2 * k], r0[2 * k + 1], hf2[k], d0); d1 = dot2pb(r0[2 * k + 2], r0[2 * k + 3], hf2[k + 1], d1);
;                     d2 = dot2pb(r0[2 * k + 4], r0[2 * k + 5], hf2[k + 2], d2); d3 = dot2pb(r0[2 * k + 6], r0[2 * k + 7], hf2[k + 3], d3); } }
;             {   const v6u_t p1 = (v6u_t){u1.z, u1.w, u2.x, u2.y, u2.z, u2.w};
;                 const v32bf_t r1 = __builtin_amdgcn_cvt_scalef32_pk32_bf16_fp6(p1, 1.0f);
; #pragma unroll
;                 for (int k = 0; k < 16; k += 4) { d0 = dot2pb(r1[2 * k], r1[2 * k + 1], hf2[16 + k], d0); d1 = dot2pb(r1[2 * k + 2], r1[2 * k + 3], hf2[16 + k + 1], d1);
;                     d2 = dot2pb(r1[2 * k + 4], r1[2 * k + 5], hf2[16 + k + 2], d2); d3 = dot2pb(r1[2 * k + 6], r1[2 * k + 7], hf2[16 + k + 3], d3); } }
;             const float d = row16_sum((d0 + d1) + (d2 + d3)) * FP6_INV;
	v_cvt_scalef32_pk32_bf16_fp6 v[0:15], v[38:43], 1.0
	v_dot2c_f32_bf16_e32 v23, v0, v192
	v_dot2c_f32_bf16_e32 v25, v1, v193
	v_dot2c_f32_bf16_e32 v22, v2, v194
	v_dot2c_f32_bf16_e32 v24, v3, v195
	v_dot2c_f32_bf16_e32 v23, v4, v196
	v_dot2c_f32_bf16_e32 v25, v5, v197
	v_dot2c_f32_bf16_e32 v22, v6, v198
	v_dot2c_f32_bf16_e32 v24, v7, v199
	v_dot2c_f32_bf16_e32 v23, v8, v200
	v_dot2c_f32_bf16_e32 v25, v9, v201
	v_dot2c_f32_bf16_e32 v22, v10, v202
	v_dot2c_f32_bf16_e32 v24, v11, v203
	v_dot2c_f32_bf16_e32 v23, v12, v204
	v_dot2c_f32_bf16_e32 v25, v13, v205
	v_dot2c_f32_bf16_e32 v22, v14, v206
	v_dot2c_f32_bf16_e32 v24, v15, v207
	s_nop 2
	v_pk_add_f32 v[0:1], v[24:25], v[22:23]
	s_nop 0
	v_add_f32_e32 v0, v0, v1
	s_nop 1
	v_add_f32_dpp v0, v0, v0 quad_perm:[1,0,3,2] row_mask:0xf bank_mask:0xf bound_ctrl:1
	s_nop 1
	v_add_f32_dpp v0, v0, v0 quad_perm:[2,3,0,1] row_mask:0xf bank_mask:0xf bound_ctrl:1
	s_nop 1
	v_add_f32_dpp v0, v0, v0 row_half_mirror row_mask:0xf bank_mask:0xf bound_ctrl:1
	s_nop 1
	v_add_f32_dpp v0, v0, v0 row_mirror row_mask:0xf bank_mask:0xf bound_ctrl:1
	s_waitcnt lgkmcnt(0)
	v_cndmask_b32_e64 v208, v208, v0, s[52:53]
	v_cndmask_b32_e64 v209, v209, v57, s[52:53]
	ds_read_b32 v56, v61
	ds_read_b32 v57, v61 offset:512
	v_add_u32_e32 v61, 16, v61
	s_add_i32 s1, s1, 1
	s_waitcnt lgkmcnt(1)
	v_mad_u32_u24 v0, v56, s14, v92
	global_load_dwordx4 v[32:35], v0, s[46:47]
	global_load_dwordx4 v[36:39], v0, s[46:47] offset:16
	global_load_dwordx4 v[40:43], v0, s[46:47] offset:32
	s_waitcnt vmcnt(4)
	v_cvt_scalef32_pk32_bf16_fp6 v[0:15], v[44:49], 1.0
	v_dot2_f32_bf16 v23, v0, v212, 0
	v_dot2_f32_bf16 v25, v1, v213, 0
	v_dot2_f32_bf16 v22, v2, v214, 0
	v_dot2_f32_bf16 v24, v3, v215, 0
	v_dot2c_f32_bf16_e32 v23, v4, v218
	v_dot2c_f32_bf16_e32 v25, v5, v219
	v_dot2c_f32_bf16_e32 v22, v6, v220
	v_dot2c_f32_bf16_e32 v24, v7, v221
	v_dot2c_f32_bf16_e32 v23, v8, v222
	v_dot2c_f32_bf16_e32 v25, v9, v223
	v_dot2c_f32_bf16_e32 v22, v10, v224
	v_dot2c_f32_bf16_e32 v24, v11, v225
	v_dot2c_f32_bf16_e32 v23, v12, v226
	v_dot2c_f32_bf16_e32 v25, v13, v227
	v_dot2c_f32_bf16_e32 v22, v14, v228
	v_dot2c_f32_bf16_e32 v24, v15, v229
	s_waitcnt vmcnt(3)
	v_cvt_scalef32_pk32_bf16_fp6 v[0:15], v[50:55], 1.0
	v_dot2c_f32_bf16_e32 v23, v0, v230
	v_dot2c_f32_bf16_e32 v25, v1, v231
	v_dot2c_f32_bf16_e32 v22, v2, v232
	v_dot2c_f32_bf16_e32 v24, v3, v233
	v_dot2c_f32_bf16_e32 v23, v4, v234
	v_dot2c_f32_bf16_e32 v25, v5, v235
	v_dot2c_f32_bf16_e32 v22, v6, v236
	v_dot2c_f32_bf16_e32 v24, v7, v237
	v_dot2c_f32_bf16_e32 v23, v8, v238
	v_dot2c_f32_bf16_e32 v25, v9, v239
	v_dot2c_f32_bf16_e32 v22, v10, v240
	v_dot2c_f32_bf16_e32 v24, v11, v241
	v_dot2c_f32_bf16_e32 v23, v12, v242
	v_dot2c_f32_bf16_e32 v25, v13, v243
	v_dot2c_f32_bf16_e32 v22, v14, v244
	v_dot2c_f32_bf16_e32 v24, v15, v245
	s_nop 2
	v_pk_add_f32 v[0:1], v[24:25], v[22:23]
	s_nop 0
	v_add_f32_e32 v0, v0, v1
	s_nop 1
	v_add_f32_dpp v0, v0, v0 quad_perm:[1,0,3,2] row_mask:0xf bank_mask:0xf bound_ctrl:1
	s_nop 1
	v_add_f32_dpp v0, v0, v0 quad_perm:[2,3,0,1] row_mask:0xf bank_mask:0xf bound_ctrl:1
	s_nop 1
	v_add_f32_dpp v0, v0, v0 row_half_mirror row_mask:0xf bank_mask:0xf bound_ctrl:1
	s_nop 1
	v_add_f32_dpp v0, v0, v0 row_mirror row_mask:0xf bank_mask:0xf bound_ctrl:1
	s_waitcnt lgkmcnt(0)
	v_cndmask_b32_e64 v210, v210, v0, s[52:53]
	v_cndmask_b32_e64 v211, v211, v59, s[52:53]
	ds_read_b32 v58, v61 offset:1520
	ds_read_b32 v59, v61 offset:2032
	s_waitcnt lgkmcnt(1)
	v_mad_u32_u24 v0, v58, s14, v92
	global_load_dwordx4 v[44:47], v0, s[46:47]
	global_load_dwordx4 v[48:51], v0, s[46:47] offset:16
	global_load_dwordx4 v[52:55], v0, s[46:47] offset:32
	s_waitcnt vmcnt(4)
	v_cvt_scalef32_pk32_bf16_fp6 v[0:15], v[32:37], 1.0
	v_dot2_f32_bf16 v23, v0, v95, 0
	v_dot2_f32_bf16 v25, v1, v159, 0
	v_dot2_f32_bf16 v22, v2, v160, 0
	v_dot2_f32_bf16 v24, v3, v161, 0
	v_dot2c_f32_bf16_e32 v23, v4, v180
	v_dot2c_f32_bf16_e32 v25, v5, v181
	v_dot2c_f32_bf16_e32 v22, v6, v182
	v_dot2c_f32_bf16_e32 v24, v7, v183
	v_dot2c_f32_bf16_e32 v23, v8, v184
	v_dot2c_f32_bf16_e32 v25, v9, v185
	v_dot2c_f32_bf16_e32 v22, v10, v186
	v_dot2c_f32_bf16_e32 v24, v11, v187
	v_dot2c_f32_bf16_e32 v23, v12, v188
	v_dot2c_f32_bf16_e32 v25, v13, v189
	v_dot2c_f32_bf16_e32 v22, v14, v190
	v_dot2c_f32_bf16_e32 v24, v15, v191
	s_waitcnt vmcnt(3)
	v_cvt_scalef32_pk32_bf16_fp6 v[0:15], v[38:43], 1.0
	v_dot2c_f32_bf16_e32 v23, v0, v192
	v_dot2c_f32_bf16_e32 v25, v1, v193
	v_dot2c_f32_bf16_e32 v22, v2, v194
	v_dot2c_f32_bf16_e32 v24, v3, v195
	v_dot2c_f32_bf16_e32 v23, v4, v196
	v_dot2c_f32_bf16_e32 v25, v5, v197
	v_dot2c_f32_bf16_e32 v22, v6, v198
	v_dot2c_f32_bf16_e32 v24, v7, v199
	v_dot2c_f32_bf16_e32 v23, v8, v200
	v_dot2c_f32_bf16_e32 v25, v9, v201
	v_dot2c_f32_bf16_e32 v22, v10, v202
	v_dot2c_f32_bf16_e32 v24, v11, v203
	v_dot2c_f32_bf16_e32 v23, v12, v204
	v_dot2c_f32_bf16_e32 v25, v13, v205
	v_dot2c_f32_bf16_e32 v22, v14, v206
	v_dot2c_f32_bf16_e32 v24, v15, v207
	s_nop 2
	v_pk_add_f32 v[0:1], v[24:25], v[22:23]
	s_nop 0
	v_add_f32_e32 v0, v0, v1
	s_nop 1
	v_add_f32_dpp v0, v0, v0 quad_perm:[1,0,3,2] row_mask:0xf bank_mask:0xf bound_ctrl:1
	s_nop 1
	v_add_f32_dpp v0, v0, v0 quad_perm:[2,3,0,1] row_mask:0xf bank_mask:0xf bound_ctrl:1
	s_nop 1
	v_add_f32_dpp v0, v0, v0 row_half_mirror row_mask:0xf bank_mask:0xf bound_ctrl:1
	s_nop 1
	v_add_f32_dpp v0, v0, v0 row_mirror row_mask:0xf bank_mask:0xf bound_ctrl:1
	s_waitcnt lgkmcnt(0)
	v_cndmask_b32_e64 v208, v208, v0, s[54:55]
	v_cndmask_b32_e64 v209, v209, v57, s[54:55]
	ds_read_b32 v56, v61
	ds_read_b32 v57, v61 offset:512
	v_add_u32_e32 v61, 16, v61
	s_add_i32 s1, s1, 1
	s_waitcnt lgkmcnt(1)
; __device__ __forceinline__ float gelu1(float v) { const f32x2 r = gelu_pk((f32x2){v, v}); return r.x; }
; __device__ __forceinline__ float dot2pb(__bf16 x0, __bf16 x1, unsigned h, float c) { bf2_t x; x[0] = x0; x[1] = x1; bf2_t y; __builtin_memcpy(&y, &h, 4); return __builtin_amdgcn_fdot2_f32_bf16(x, y, c, false); }
; __device__ void ph_peer(const float* __restrict__ SC, const bf16_t* __restrict__ H  , const float* __restrict__ gffn, const unsigned char* __restrict__ U, const unsigned char* __restrict__ V, float* X, const float* __restrict__ fgain) {
;     ...
;             const u32x4* up = (const u32x4*)(U + (size_t)e * 768 + 48 * sub);
;             const u32x4 u0 = up[0], u1 = up[1], u2 = up[2];
;             u32x2 vw[2][3];
; #pragma unroll
;             for (int r = 0; r < 2; ++r) { const int ea = __builtin_amdgcn_readlane(e, 32 * r), eb = __builtin_amdgcn_readlane(e, 32 * r + 16);
;                 const u32x2* vp = (const u32x2*)(V + (size_t)(half ? eb : ea) * 768 + 24 * c32); vw[r][0] = vp[0]; vw[r][1] = vp[1]; vw[r][2] = vp[2]; }
;             float d0 = 0.f, d1 = 0.f, d2 = 0.f, d3 = 0.f;
;             {   const v6u_t p0 = (v6u_t){u0.x, u0.y, u0.z, u0.w, u1.x, u1.y};
;                 const v32bf_t r0 = __builtin_amdgcn_cvt_scalef32_pk32_bf16_fp6(p0, 1.0f);
; #pragma unroll
;                 for (int k = 0; k < 16; k += 4) { d0 = dot2pb(r0[2 * k], r0[2 * k + 1], hf2[k], d0); d1 = dot2pb(r0[2 * k + 2], r0[2 * k + 3], hf2[k + 1], d1);
;                     d2 = dot2pb(r0[2 * k + 4], r0[2 * k + 5], hf2[k + 2], d2); d3 = dot2pb(r0[2 * k + 6], r0[2 * k + 7], hf2[k + 3], d3); } }
;             {   const v6u_t p1 = (v6u_t){u1.z, u1.w, u2.x, u2.y, u2.z, u2.w};
;                 const v32bf_t r1 = __builtin_amdgcn_cvt_scalef32_pk32_bf16_fp6(p1, 1.0f);
; #pragma unroll
;                 for (int k = 0; k < 16; k += 4) { d0 = dot2pb(r1[2 * k], r1[2 * k + 1], hf2[16 + k], d0); d1 = dot2pb(r1[2 * k + 2], r1[2 * k + 3], hf2[16 + k + 1], d1);
;                     d2 = dot2pb(r1[2 * k + 4], r1[2 * k + 5], hf2[16 + k + 2], d2); d3 = dot2pb(r1[2 * k + 6], r1[2 * k + 7], hf2[16 + k + 3], d3); } }
;             const float d = row16_sum((d0 + d1) + (d2 + d3)) * FP6_INV;
;             const float a = gt * gelu1(d) * FP6_INV;
	v_mad_u32_u24 v0, v56, s14, v92
	global_load_dwordx4 v[32:35], v0, s[46:47]
	global_load_dwordx4 v[36:39], v0, s[46:47] offset:16
	global_load_dwordx4 v[40:43], v0, s[46:47] offset:32
	s_waitcnt vmcnt(4)
	v_cvt_scalef32_pk32_bf16_fp6 v[0:15], v[44:49], 1.0
	v_dot2_f32_bf16 v23, v0, v212, 0
	v_dot2_f32_bf16 v25, v1, v213, 0
	v_dot2_f32_bf16 v22, v2, v214, 0
	v_dot2_f32_bf16 v24, v3, v215, 0
	v_dot2c_f32_bf16_e32 v23, v4, v218
	v_dot2c_f32_bf16_e32 v25, v5, v219
	v_dot2c_f32_bf16_e32 v22, v6, v220
	v_dot2c_f32_bf16_e32 v24, v7, v221
	v_dot2c_f32_bf16_e32 v23, v8, v222
	v_dot2c_f32_bf16_e32 v25, v9, v223
	v_dot2c_f32_bf16_e32 v22, v10, v224
	v_dot2c_f32_bf16_e32 v24, v11, v225
	v_dot2c_f32_bf16_e32 v23, v12, v226
	v_dot2c_f32_bf16_e32 v25, v13, v227
	v_dot2c_f32_bf16_e32 v22, v14, v228
	v_dot2c_f32_bf16_e32 v24, v15, v229
	s_waitcnt vmcnt(3)
	v_cvt_scalef32_pk32_bf16_fp6 v[0:15], v[50:55], 1.0
	v_dot2c_f32_bf16_e32 v23, v0, v230
	v_dot2c_f32_bf16_e32 v25, v1, v231
	v_dot2c_f32_bf16_e32 v22, v2, v232
	v_dot2c_f32_bf16_e32 v24, v3, v233
	v_dot2c_f32_bf16_e32 v23, v4, v234
	v_dot2c_f32_bf16_e32 v25, v5, v235
	v_dot2c_f32_bf16_e32 v22, v6, v236
	v_dot2c_f32_bf16_e32 v24, v7, v237
	v_dot2c_f32_bf16_e32 v23, v8, v238
	v_dot2c_f32_bf16_e32 v25, v9, v239
	v_dot2c_f32_bf16_e32 v22, v10, v240
	v_dot2c_f32_bf16_e32 v24, v11, v241
	v_dot2c_f32_bf16_e32 v23, v12, v242
	v_dot2c_f32_bf16_e32 v25, v13, v243
	v_dot2c_f32_bf16_e32 v22, v14, v244
	v_dot2c_f32_bf16_e32 v24, v15, v245
	s_nop 2
	v_pk_add_f32 v[0:1], v[24:25], v[22:23]
	s_nop 0
	v_add_f32_e32 v0, v0, v1
	s_nop 1
	v_add_f32_dpp v0, v0, v0 quad_perm:[1,0,3,2] row_mask:0xf bank_mask:0xf bound_ctrl:1
	s_nop 1
	v_add_f32_dpp v0, v0, v0 quad_perm:[2,3,0,1] row_mask:0xf bank_mask:0xf bound_ctrl:1
	s_nop 1
	v_add_f32_dpp v0, v0, v0 row_half_mirror row_mask:0xf bank_mask:0xf bound_ctrl:1
	s_nop 1
	v_add_f32_dpp v0, v0, v0 row_mirror row_mask:0xf bank_mask:0xf bound_ctrl:1
	s_waitcnt lgkmcnt(0)
	v_cndmask_b32_e64 v210, v210, v0, s[54:55]
	v_cndmask_b32_e64 v211, v211, v59, s[54:55]
	ds_read_b32 v58, v61 offset:1520
	ds_read_b32 v59, v61 offset:2032
	s_waitcnt lgkmcnt(1)
	v_mad_u32_u24 v0, v58, s14, v92
	global_load_dwordx4 v[44:47], v0, s[46:47]
	global_load_dwordx4 v[48:51], v0, s[46:47] offset:16
	global_load_dwordx4 v[52:55], v0, s[46:47] offset:32
	s_waitcnt vmcnt(4)
	v_cvt_scalef32_pk32_bf16_fp6 v[0:15], v[32:37], 1.0
	v_dot2_f32_bf16 v23, v0, v95, 0
	v_dot2_f32_bf16 v25, v1, v159, 0
	v_dot2_f32_bf16 v22, v2, v160, 0
	v_dot2_f32_bf16 v24, v3, v161, 0
	v_dot2c_f32_bf16_e32 v23, v4, v180
	v_dot2c_f32_bf16_e32 v25, v5, v181
	v_dot2c_f32_bf16_e32 v22, v6, v182
	v_dot2c_f32_bf16_e32 v24, v7, v183
	v_dot2c_f32_bf16_e32 v23, v8, v184
	v_dot2c_f32_bf16_e32 v25, v9, v185
	v_dot2c_f32_bf16_e32 v22, v10, v186
	v_dot2c_f32_bf16_e32 v24, v11, v187
	v_dot2c_f32_bf16_e32 v23, v12, v188
	v_dot2c_f32_bf16_e32 v25, v13, v189
	v_dot2c_f32_bf16_e32 v22, v14, v190
	v_dot2c_f32_bf16_e32 v24, v15, v191
	s_waitcnt vmcnt(3)
	v_cvt_scalef32_pk32_bf16_fp6 v[0:15], v[38:43], 1.0
	v_dot2c_f32_bf16_e32 v23, v0, v192
	v_dot2c_f32_bf16_e32 v25, v1, v193
	v_dot2c_f32_bf16_e32 v22, v2, v194
	v_dot2c_f32_bf16_e32 v24, v3, v195
	v_dot2c_f32_bf16_e32 v23, v4, v196
	v_dot2c_f32_bf16_e32 v25, v5, v197
	v_dot2c_f32_bf16_e32 v22, v6, v198
	v_dot2c_f32_bf16_e32 v24, v7, v199
	v_dot2c_f32_bf16_e32 v23, v8, v200
	v_dot2c_f32_bf16_e32 v25, v9, v201
	v_dot2c_f32_bf16_e32 v22, v10, v202
	v_dot2c_f32_bf16_e32 v24, v11, v203
	v_dot2c_f32_bf16_e32 v23, v12, v204
	v_dot2c_f32_bf16_e32 v25, v13, v205
	v_dot2c_f32_bf16_e32 v22, v14, v206
	v_dot2c_f32_bf16_e32 v24, v15, v207
	s_nop 2
	v_pk_add_f32 v[0:1], v[24:25], v[22:23]
	s_nop 0
	v_add_f32_e32 v0, v0, v1
	s_nop 1
	v_add_f32_dpp v0, v0, v0 quad_perm:[1,0,3,2] row_mask:0xf bank_mask:0xf bound_ctrl:1
	s_nop 1
	v_add_f32_dpp v0, v0, v0 quad_perm:[2,3,0,1] row_mask:0xf bank_mask:0xf bound_ctrl:1
	s_nop 1
	v_add_f32_dpp v0, v0, v0 row_half_mirror row_mask:0xf bank_mask:0xf bound_ctrl:1
	s_nop 1
	v_add_f32_dpp v0, v0, v0 row_mirror row_mask:0xf bank_mask:0xf bound_ctrl:1
	s_waitcnt lgkmcnt(0)
	v_cndmask_b32_e64 v0, v208, v0, s[56:57]
	v_cndmask_b32_e64 v209, v209, v57, s[56:57]
	v_mul_f32_e32 v0, 0x3caaaaab, v0
	v_and_b32_e32 v2, 0x7fffffff, v0
	v_pk_fma_f32 v[2:3], v[2:3], s[16:17], 1.0 op_sel_hi:[0,0,0]
	v_rcp_f32_e32 v2, v2
	v_rcp_f32_e32 v3, v3
	v_mul_f32_e32 v1, v0, v0
	v_mul_f32_e32 v1, 0xbf38aa3b, v1
	v_cmp_gt_f32_e32 vcc, 0, v0
	v_pk_fma_f32 v[4:5], v[2:3], s[24:25], v[130:131] op_sel_hi:[1,0,0]
	s_nop 0
	v_pk_fma_f32 v[4:5], v[2:3], v[4:5], s[28:29] op_sel_hi:[1,1,0]
	s_nop 0
	v_pk_fma_f32 v[4:5], v[2:3], v[4:5], s[30:31] op_sel_hi:[1,1,0]
	s_nop 0
	v_pk_fma_f32 v[4:5], v[2:3], v[4:5], s[36:37] op_sel_hi:[1,1,0]
	s_nop 0
	v_pk_mul_f32 v[2:3], v[2:3], v[4:5]
	v_exp_f32_e32 v4, v1
	s_nop 0
	v_pk_mul_f32 v[2:3], v[4:5], v[2:3] op_sel_hi:[0,1]
	v_pk_fma_f32 v[4:5], v[0:1], v[2:3], v[0:1] op_sel_hi:[0,1,1] neg_lo:[1,0,0] neg_hi:[1,0,0]
	v_mul_f32_e32 v0, v0, v2
	v_cndmask_b32_e32 v0, v4, v0, vcc
	v_mul_f32_e32 v0, v0, v209
	v_mul_f32_e32 v60, 0x3caaaaab, v0
	v_add_u32_e32 v62, v61, v155
	ds_write_b32 v62, v60 offset:960
	ds_read_b32 v56, v61
	ds_read_b32 v57, v61 offset:512
	v_add_u32_e32 v61, 16, v61
	s_add_i32 s1, s1, 1
	s_waitcnt lgkmcnt(1)
	v_mad_u32_u24 v0, v56, s14, v92
	global_load_dwordx4 v[32:35], v0, s[46:47]
	global_load_dwordx4 v[36:39], v0, s[46:47] offset:16
	global_load_dwordx4 v[40:43], v0, s[46:47] offset:32
	s_waitcnt vmcnt(4)
; __device__ __forceinline__ float gelu1(float v) { const f32x2 r = gelu_pk((f32x2){v, v}); return r.x; }
; __device__ __forceinline__ float dot2pb(__bf16 x0, __bf16 x1, unsigned h, float c) { bf2_t x; x[0] = x0; x[1] = x1; bf2_t y; __builtin_memcpy(&y, &h, 4); return __builtin_amdgcn_fdot2_f32_bf16(x, y, c, false); }
; __device__ void ph_peer(const float* __restrict__ SC, const bf16_t* __restrict__ H  , const float* __restrict__ gffn, const unsigned char* __restrict__ U, const unsigned char* __restrict__ V, float* X, const float* __restrict__ fgain) {
;     ...
;             const u32x4* up = (const u32x4*)(U + (size_t)e * 768 + 48 * sub);
;             const u32x4 u0 = up[0], u1 = up[1], u2 = up[2];
;             u32x2 vw[2][3];
; #pragma unroll
;             for (int r = 0; r < 2; ++r) { const int ea = __builtin_amdgcn_readlane(e, 32 * r), eb = __builtin_amdgcn_readlane(e, 32 * r + 16);
;                 const u32x2* vp = (const u32x2*)(V + (size_t)(half ? eb : ea) * 768 + 24 * c32); vw[r][0] = vp[0]; vw[r][1] = vp[1]; vw[r][2] = vp[2]; }
;             float d0 = 0.f, d1 = 0.f, d2 = 0.f, d3 = 0.f;
;             {   const v6u_t p0 = (v6u_t){u0.x, u0.y, u0.z, u0.w, u1.x, u1.y};
;                 const v32bf_t r0 = __builtin_amdgcn_cvt_scalef32_pk32_bf16_fp6(p0, 1.0f);
; #pragma unroll
;                 for (int k = 0; k < 16; k += 4) { d0 = dot2pb(r0[2 * k], r0[2 * k + 1], hf2[k], d0); d1 = dot2pb(r0[2 * k + 2], r0[2 * k + 3], hf2[k + 1], d1);
;                     d2 = dot2pb(r0[2 * k + 4], r0[2 * k + 5], hf2[k + 2], d2); d3 = dot2pb(r0[2 * k + 6], r0[2 * k + 7], hf2[k + 3], d3); } }
;             {   const v6u_t p1 = (v6u_t){u1.z, u1.w, u2.x, u2.y, u2.z, u2.w};
;                 const v32bf_t r1 = __builtin_amdgcn_cvt_scalef32_pk32_bf16_fp6(p1, 1.0f);
; #pragma unroll
;                 for (int k = 0; k < 16; k += 4) { d0 = dot2pb(r1[2 * k], r1[2 * k + 1], hf2[16 + k], d0); d1 = dot2pb(r1[2 * k + 2], r1[2 * k + 3], hf2[16 + k + 1], d1);
;                     d2 = dot2pb(r1[2 * k + 4], r1[2 * k + 5], hf2[16 + k + 2], d2); d3 = dot2pb(r1[2 * k + 6], r1[2 * k + 7], hf2[16 + k + 3], d3); } }
;             const float d = row16_sum((d0 + d1) + (d2 + d3)) * FP6_INV;
;             const float a = gt * gelu1(d) * FP6_INV;
	v_cvt_scalef32_pk32_bf16_fp6 v[0:15], v[44:49], 1.0
	v_dot2_f32_bf16 v23, v0, v212, 0
	v_dot2_f32_bf16 v25, v1, v213, 0
	v_dot2_f32_bf16 v22, v2, v214, 0
	v_dot2_f32_bf16 v24, v3, v215, 0
	v_dot2c_f32_bf16_e32 v23, v4, v218
	v_dot2c_f32_bf16_e32 v25, v5, v219
	v_dot2c_f32_bf16_e32 v22, v6, v220
	v_dot2c_f32_bf16_e32 v24, v7, v221
	v_dot2c_f32_bf16_e32 v23, v8, v222
	v_dot2c_f32_bf16_e32 v25, v9, v223
	v_dot2c_f32_bf16_e32 v22, v10, v224
	v_dot2c_f32_bf16_e32 v24, v11, v225
	v_dot2c_f32_bf16_e32 v23, v12, v226
	v_dot2c_f32_bf16_e32 v25, v13, v227
	v_dot2c_f32_bf16_e32 v22, v14, v228
	v_dot2c_f32_bf16_e32 v24, v15, v229
	s_waitcnt vmcnt(3)
	v_cvt_scalef32_pk32_bf16_fp6 v[0:15], v[50:55], 1.0
	v_dot2c_f32_bf16_e32 v23, v0, v230
	v_dot2c_f32_bf16_e32 v25, v1, v231
	v_dot2c_f32_bf16_e32 v22, v2, v232
	v_dot2c_f32_bf16_e32 v24, v3, v233
	v_dot2c_f32_bf16_e32 v23, v4, v234
	v_dot2c_f32_bf16_e32 v25, v5, v235
	v_dot2c_f32_bf16_e32 v22, v6, v236
	v_dot2c_f32_bf16_e32 v24, v7, v237
	v_dot2c_f32_bf16_e32 v23, v8, v238
	v_dot2c_f32_bf16_e32 v25, v9, v239
	v_dot2c_f32_bf16_e32 v22, v10, v240
	v_dot2c_f32_bf16_e32 v24, v11, v241
	v_dot2c_f32_bf16_e32 v23, v12, v242
	v_dot2c_f32_bf16_e32 v25, v13, v243
	v_dot2c_f32_bf16_e32 v22, v14, v244
	v_dot2c_f32_bf16_e32 v24, v15, v245
	s_nop 2
	v_pk_add_f32 v[0:1], v[24:25], v[22:23]
	s_nop 0
	v_add_f32_e32 v0, v0, v1
	s_nop 1
	v_add_f32_dpp v0, v0, v0 quad_perm:[1,0,3,2] row_mask:0xf bank_mask:0xf bound_ctrl:1
	s_nop 1
	v_add_f32_dpp v0, v0, v0 quad_perm:[2,3,0,1] row_mask:0xf bank_mask:0xf bound_ctrl:1
	s_nop 1
	v_add_f32_dpp v0, v0, v0 row_half_mirror row_mask:0xf bank_mask:0xf bound_ctrl:1
	s_nop 1
	v_add_f32_dpp v0, v0, v0 row_mirror row_mask:0xf bank_mask:0xf bound_ctrl:1
	s_waitcnt lgkmcnt(0)
	v_cndmask_b32_e64 v0, v210, v0, s[56:57]
	v_cndmask_b32_e64 v211, v211, v59, s[56:57]
	v_mul_f32_e32 v0, 0x3caaaaab, v0
	v_and_b32_e32 v2, 0x7fffffff, v0
	v_pk_fma_f32 v[2:3], v[2:3], s[16:17], 1.0 op_sel_hi:[0,0,0]
	v_rcp_f32_e32 v2, v2
	v_rcp_f32_e32 v3, v3
	v_mul_f32_e32 v1, v0, v0
	v_mul_f32_e32 v1, 0xbf38aa3b, v1
	v_cmp_gt_f32_e32 vcc, 0, v0
	v_pk_fma_f32 v[4:5], v[2:3], s[24:25], v[130:131] op_sel_hi:[1,0,0]
	s_nop 0
	v_pk_fma_f32 v[4:5], v[2:3], v[4:5], s[28:29] op_sel_hi:[1,1,0]
	s_nop 0
	v_pk_fma_f32 v[4:5], v[2:3], v[4:5], s[30:31] op_sel_hi:[1,1,0]
	s_nop 0
	v_pk_fma_f32 v[4:5], v[2:3], v[4:5], s[36:37] op_sel_hi:[1,1,0]
	s_nop 0
	v_pk_mul_f32 v[2:3], v[2:3], v[4:5]
	v_exp_f32_e32 v4, v1
	s_nop 0
	v_pk_mul_f32 v[2:3], v[4:5], v[2:3] op_sel_hi:[0,1]
	v_pk_fma_f32 v[4:5], v[0:1], v[2:3], v[0:1] op_sel_hi:[0,1,1] neg_lo:[1,0,0] neg_hi:[1,0,0]
	v_mul_f32_e32 v0, v0, v2
	v_cndmask_b32_e32 v0, v4, v0, vcc
	v_mul_f32_e32 v0, v0, v211
	v_mul_f32_e32 v60, 0x3caaaaab, v0
	v_add_u32_e32 v62, v61, v155
	ds_write_b32 v62, v60 offset:2480
	s_cmp_lt_u32 s1, 29
	s_cbranch_scc1 .Lpeer_uloop
	ds_read_b32 v58, v61 offset:1520
	ds_read_b32 v59, v61 offset:2032
	s_waitcnt lgkmcnt(1)
	v_mad_u32_u24 v0, v58, s14, v92
	global_load_dwordx4 v[44:47], v0, s[46:47]
	global_load_dwordx4 v[48:51], v0, s[46:47] offset:16
	global_load_dwordx4 v[52:55], v0, s[46:47] offset:32
	s_waitcnt vmcnt(4)
	v_cvt_scalef32_pk32_bf16_fp6 v[0:15], v[32:37], 1.0
	v_dot2_f32_bf16 v23, v0, v95, 0
	v_dot2_f32_bf16 v25, v1, v159, 0
	v_dot2_f32_bf16 v22, v2, v160, 0
	v_dot2_f32_bf16 v24, v3, v161, 0
	v_dot2c_f32_bf16_e32 v23, v4, v180
	v_dot2c_f32_bf16_e32 v25, v5, v181
	v_dot2c_f32_bf16_e32 v22, v6, v182
	v_dot2c_f32_bf16_e32 v24, v7, v183
	v_dot2c_f32_bf16_e32 v23, v8, v184
	v_dot2c_f32_bf16_e32 v25, v9, v185
	v_dot2c_f32_bf16_e32 v22, v10, v186
	v_dot2c_f32_bf16_e32 v24, v11, v187
	v_dot2c_f32_bf16_e32 v23, v12, v188
	v_dot2c_f32_bf16_e32 v25, v13, v189
	v_dot2c_f32_bf16_e32 v22, v14, v190
	v_dot2c_f32_bf16_e32 v24, v15, v191
	s_waitcnt vmcnt(3)
	v_cvt_scalef32_pk32_bf16_fp6 v[0:15], v[38:43], 1.0
	v_dot2c_f32_bf16_e32 v23, v0, v192
	v_dot2c_f32_bf16_e32 v25, v1, v193
	v_dot2c_f32_bf16_e32 v22, v2, v194
	v_dot2c_f32_bf16_e32 v24, v3, v195
	v_dot2c_f32_bf16_e32 v23, v4, v196
	v_dot2c_f32_bf16_e32 v25, v5, v197
	v_dot2c_f32_bf16_e32 v22, v6, v198
	v_dot2c_f32_bf16_e32 v24, v7, v199
	v_dot2c_f32_bf16_e32 v23, v8, v200
	v_dot2c_f32_bf16_e32 v25, v9, v201
	v_dot2c_f32_bf16_e32 v22, v10, v202
	v_dot2c_f32_bf16_e32 v24, v11, v203
	v_dot2c_f32_bf16_e32 v23, v12, v204
	v_dot2c_f32_bf16_e32 v25, v13, v205
	v_dot2c_f32_bf16_e32 v22, v14, v206
	v_dot2c_f32_bf16_e32 v24, v15, v207
	s_nop 2
	v_pk_add_f32 v[0:1], v[24:25], v[22:23]
	s_nop 0
	v_add_f32_e32 v0, v0, v1
	s_nop 1
	v_add_f32_dpp v0, v0, v0 quad_perm:[1,0,3,2] row_mask:0xf bank_mask:0xf bound_ctrl:1
	s_nop 1
	v_add_f32_dpp v0, v0, v0 quad_perm:[2,3,0,1] row_mask:0xf bank_mask:0xf bound_ctrl:1
	s_nop 1
	v_add_f32_dpp v0, v0, v0 row_half_mirror row_mask:0xf bank_mask:0xf bound_ctrl:1
	s_nop 1
	v_add_f32_dpp v0, v0, v0 row_mirror row_mask:0xf bank_mask:0xf bound_ctrl:1
	s_waitcnt lgkmcnt(0)
	v_cndmask_b32_e64 v208, v208, v0, s[50:51]
	v_cndmask_b32_e64 v209, v209, v57, s[50:51]
	ds_read_b32 v56, v61
	ds_read_b32 v57, v61 offset:512
	v_add_u32_e32 v61, 16, v61
	s_add_i32 s1, s1, 1
	s_waitcnt lgkmcnt(1)
	v_mad_u32_u24 v0, v56, s14, v92
	global_load_dwordx4 v[32:35], v0, s[46:47]
	global_load_dwordx4 v[36:39], v0, s[46:47] offset:16
	global_load_dwordx4 v[40:43], v0, s[46:47] offset:32
	s_waitcnt vmcnt(4)
; __device__ __forceinline__ float gelu1(float v) { const f32x2 r = gelu_pk((f32x2){v, v}); return r.x; }
; __device__ __forceinline__ float dot2pb(__bf16 x0, __bf16 x1, unsigned h, float c) { bf2_t x; x[0] = x0; x[1] = x1; bf2_t y; __builtin_memcpy(&y, &h, 4); return __builtin_amdgcn_fdot2_f32_bf16(x, y, c, false); }
; __device__ void ph_peer(const float* __restrict__ SC, const bf16_t* __restrict__ H  , const float* __restrict__ gffn, const unsigned char* __restrict__ U, const unsigned char* __restrict__ V, float* X, const float* __restrict__ fgain) {
;     ...
;             const u32x4* up = (const u32x4*)(U + (size_t)e * 768 + 48 * sub);
;             const u32x4 u0 = up[0], u1 = up[1], u2 = up[2];
;             u32x2 vw[2][3];
; #pragma unroll
;             for (int r = 0; r < 2; ++r) { const int ea = __builtin_amdgcn_readlane(e, 32 * r), eb = __builtin_amdgcn_readlane(e, 32 * r + 16);
;                 const u32x2* vp = (const u32x2*)(V + (size_t)(half ? eb : ea) * 768 + 24 * c32); vw[r][0] = vp[0]; vw[r][1] = vp[1]; vw[r][2] = vp[2]; }
;             float d0 = 0.f, d1 = 0.f, d2 = 0.f, d3 = 0.f;
;             {   const v6u_t p0 = (v6u_t){u0.x, u0.y, u0.z, u0.w, u1.x, u1.y};
;                 const v32bf_t r0 = __builtin_amdgcn_cvt_scalef32_pk32_bf16_fp6(p0, 1.0f);
; #pragma unroll
;                 for (int k = 0; k < 16; k += 4) { d0 = dot2pb(r0[2 * k], r0[2 * k + 1], hf2[k], d0); d1 = dot2pb(r0[2 * k + 2], r0[2 * k + 3], hf2[k + 1], d1);
;                     d2 = dot2pb(r0[2 * k + 4], r0[2 * k + 5], hf2[k + 2], d2); d3 = dot2pb(r0[2 * k + 6], r0[2 * k + 7], hf2[k + 3], d3); } }
;             {   const v6u_t p1 = (v6u_t){u1.z, u1.w, u2.x, u2.y, u2.z, u2.w};
;                 const v32bf_t r1 = __builtin_amdgcn_cvt_scalef32_pk32_bf16_fp6(p1, 1.0f);
; #pragma unroll
;                 for (int k = 0; k < 16; k += 4) { d0 = dot2pb(r1[2 * k], r1[2 * k + 1], hf2[16 + k], d0); d1 = dot2pb(r1[2 * k + 2], r1[2 * k + 3], hf2[16 + k + 1], d1);
;                     d2 = dot2pb(r1[2 * k + 4], r1[2 * k + 5], hf2[16 + k + 2], d2); d3 = dot2pb(r1[2 * k + 6], r1[2 * k + 7], hf2[16 + k + 3], d3); } }
;             const float d = row16_sum((d0 + d1) + (d2 + d3)) * FP6_INV;
;             const float a = gt * gelu1(d) * FP6_INV;
	v_cvt_scalef32_pk32_bf16_fp6 v[0:15], v[44:49], 1.0
	v_dot2_f32_bf16 v23, v0, v212, 0
	v_dot2_f32_bf16 v25, v1, v213, 0
	v_dot2_f32_bf16 v22, v2, v214, 0
	v_dot2_f32_bf16 v24, v3, v215, 0
	v_dot2c_f32_bf16_e32 v23, v4, v218
	v_dot2c_f32_bf16_e32 v25, v5, v219
	v_dot2c_f32_bf16_e32 v22, v6, v220
	v_dot2c_f32_bf16_e32 v24, v7, v221
	v_dot2c_f32_bf16_e32 v23, v8, v222
	v_dot2c_f32_bf16_e32 v25, v9, v223
	v_dot2c_f32_bf16_e32 v22, v10, v224
	v_dot2c_f32_bf16_e32 v24, v11, v225
	v_dot2c_f32_bf16_e32 v23, v12, v226
	v_dot2c_f32_bf16_e32 v25, v13, v227
	v_dot2c_f32_bf16_e32 v22, v14, v228
	v_dot2c_f32_bf16_e32 v24, v15, v229
	s_waitcnt vmcnt(3)
	v_cvt_scalef32_pk32_bf16_fp6 v[0:15], v[50:55], 1.0
	v_dot2c_f32_bf16_e32 v23, v0, v230
	v_dot2c_f32_bf16_e32 v25, v1, v231
	v_dot2c_f32_bf16_e32 v22, v2, v232
	v_dot2c_f32_bf16_e32 v24, v3, v233
	v_dot2c_f32_bf16_e32 v23, v4, v234
	v_dot2c_f32_bf16_e32 v25, v5, v235
	v_dot2c_f32_bf16_e32 v22, v6, v236
	v_dot2c_f32_bf16_e32 v24, v7, v237
	v_dot2c_f32_bf16_e32 v23, v8, v238
	v_dot2c_f32_bf16_e32 v25, v9, v239
	v_dot2c_f32_bf16_e32 v22, v10, v240
	v_dot2c_f32_bf16_e32 v24, v11, v241
	v_dot2c_f32_bf16_e32 v23, v12, v242
	v_dot2c_f32_bf16_e32 v25, v13, v243
	v_dot2c_f32_bf16_e32 v22, v14, v244
	v_dot2c_f32_bf16_e32 v24, v15, v245
	s_nop 2
	v_pk_add_f32 v[0:1], v[24:25], v[22:23]
	s_nop 0
	v_add_f32_e32 v0, v0, v1
	s_nop 1
	v_add_f32_dpp v0, v0, v0 quad_perm:[1,0,3,2] row_mask:0xf bank_mask:0xf bound_ctrl:1
	s_nop 1
	v_add_f32_dpp v0, v0, v0 quad_perm:[2,3,0,1] row_mask:0xf bank_mask:0xf bound_ctrl:1
	s_nop 1
	v_add_f32_dpp v0, v0, v0 row_half_mirror row_mask:0xf bank_mask:0xf bound_ctrl:1
	s_nop 1
	v_add_f32_dpp v0, v0, v0 row_mirror row_mask:0xf bank_mask:0xf bound_ctrl:1
	s_waitcnt lgkmcnt(0)
	v_cndmask_b32_e64 v210, v210, v0, s[50:51]
	v_cndmask_b32_e64 v211, v211, v59, s[50:51]
	ds_read_b32 v58, v61 offset:1520
	ds_read_b32 v59, v61 offset:2032
	s_waitcnt lgkmcnt(1)
	v_mad_u32_u24 v0, v58, s14, v92
	global_load_dwordx4 v[44:47], v0, s[46:47]
	global_load_dwordx4 v[48:51], v0, s[46:47] offset:16
	global_load_dwordx4 v[52:55], v0, s[46:47] offset:32
	s_waitcnt vmcnt(4)
	v_cvt_scalef32_pk32_bf16_fp6 v[0:15], v[32:37], 1.0
	v_dot2_f32_bf16 v23, v0, v95, 0
	v_dot2_f32_bf16 v25, v1, v159, 0
	v_dot2_f32_bf16 v22, v2, v160, 0
	v_dot2_f32_bf16 v24, v3, v161, 0
	v_dot2c_f32_bf16_e32 v23, v4, v180
	v_dot2c_f32_bf16_e32 v25, v5, v181
	v_dot2c_f32_bf16_e32 v22, v6, v182
	v_dot2c_f32_bf16_e32 v24, v7, v183
	v_dot2c_f32_bf16_e32 v23, v8, v184
	v_dot2c_f32_bf16_e32 v25, v9, v185
	v_dot2c_f32_bf16_e32 v22, v10, v186
	v_dot2c_f32_bf16_e32 v24, v11, v187
	v_dot2c_f32_bf16_e32 v23, v12, v188
	v_dot2c_f32_bf16_e32 v25, v13, v189
	v_dot2c_f32_bf16_e32 v22, v14, v190
	v_dot2c_f32_bf16_e32 v24, v15, v191
	s_waitcnt vmcnt(3)
	v_cvt_scalef32_pk32_bf16_fp6 v[0:15], v[38:43], 1.0
	v_dot2c_f32_bf16_e32 v23, v0, v192
	v_dot2c_f32_bf16_e32 v25, v1, v193
	v_dot2c_f32_bf16_e32 v22, v2, v194
	v_dot2c_f32_bf16_e32 v24, v3, v195
	v_dot2c_f32_bf16_e32 v23, v4, v196
	v_dot2c_f32_bf16_e32 v25, v5, v197
	v_dot2c_f32_bf16_e32 v22, v6, v198
	v_dot2c_f32_bf16_e32 v24, v7, v199
	v_dot2c_f32_bf16_e32 v23, v8, v200
	v_dot2c_f32_bf16_e32 v25, v9, v201
	v_dot2c_f32_bf16_e32 v22, v10, v202
	v_dot2c_f32_bf16_e32 v24, v11, v203
	v_dot2c_f32_bf16_e32 v23, v12, v204
	v_dot2c_f32_bf16_e32 v25, v13, v205
	v_dot2c_f32_bf16_e32 v22, v14, v206
	v_dot2c_f32_bf16_e32 v24, v15, v207
	s_nop 2
	v_pk_add_f32 v[0:1], v[24:25], v[22:23]
	s_nop 0
	v_add_f32_e32 v0, v0, v1
	s_nop 1
	v_add_f32_dpp v0, v0, v0 quad_perm:[1,0,3,2] row_mask:0xf bank_mask:0xf bound_ctrl:1
	s_nop 1
	v_add_f32_dpp v0, v0, v0 quad_perm:[2,3,0,1] row_mask:0xf bank_mask:0xf bound_ctrl:1
	s_nop 1
	v_add_f32_dpp v0, v0, v0 row_half_mirror row_mask:0xf bank_mask:0xf bound_ctrl:1
	s_nop 1
	v_add_f32_dpp v0, v0, v0 row_mirror row_mask:0xf bank_mask:0xf bound_ctrl:1
	s_waitcnt lgkmcnt(0)
	v_cndmask_b32_e64 v208, v208, v0, s[52:53]
	v_cndmask_b32_e64 v209, v209, v57, s[52:53]
	ds_read_b32 v56, v61
	ds_read_b32 v57, v61 offset:512
	v_add_u32_e32 v61, 16, v61
	s_add_i32 s1, s1, 1
	s_waitcnt lgkmcnt(1)
	v_mad_u32_u24 v0, v56, s14, v92
	global_load_dwordx4 v[32:35], v0, s[46:47]
	global_load_dwordx4 v[36:39], v0, s[46:47] offset:16
	global_load_dwordx4 v[40:43], v0, s[46:47] offset:32
	s_waitcnt vmcnt(4)
	v_cvt_scalef32_pk32_bf16_fp6 v[0:15], v[44:49], 1.0
	v_dot2_f32_bf16 v23, v0, v212, 0
	v_dot2_f32_bf16 v25, v1, v213, 0
	v_dot2_f32_bf16 v22, v2, v214, 0
	v_dot2_f32_bf16 v24, v3, v215, 0
	v_dot2c_f32_bf16_e32 v23, v4, v218
	v_dot2c_f32_bf16_e32 v25, v5, v219
	v_dot2c_f32_bf16_e32 v22, v6, v220
	v_dot2c_f32_bf16_e32 v24, v7, v221
	v_dot2c_f32_bf16_e32 v23, v8, v222
	v_dot2c_f32_bf16_e32 v25, v9, v223
	v_dot2c_f32_bf16_e32 v22, v10, v224
	v_dot2c_f32_bf16_e32 v24, v11, v225
	v_dot2c_f32_bf16_e32 v23, v12, v226
	v_dot2c_f32_bf16_e32 v25, v13, v227
	v_dot2c_f32_bf16_e32 v22, v14, v228
	v_dot2c_f32_bf16_e32 v24, v15, v229
	s_waitcnt vmcnt(3)
	v_cvt_scalef32_pk32_bf16_fp6 v[0:15], v[50:55], 1.0
	v_dot2c_f32_bf16_e32 v23, v0, v230
	v_dot2c_f32_bf16_e32 v25, v1, v231
	v_dot2c_f32_bf16_e32 v22, v2, v232
	v_dot2c_f32_bf16_e32 v24, v3, v233
	v_dot2c_f32_bf16_e32 v23, v4, v234
	v_dot2c_f32_bf16_e32 v25, v5, v235
	v_dot2c_f32_bf16_e32 v22, v6, v236
	v_dot2c_f32_bf16_e32 v24, v7, v237
	v_dot2c_f32_bf16_e32 v23, v8, v238
	v_dot2c_f32_bf16_e32 v25, v9, v239
	v_dot2c_f32_bf16_e32 v22, v10, v240
	v_dot2c_f32_bf16_e32 v24, v11, v241
	v_dot2c_f32_bf16_e32 v23, v12, v242
	v_dot2c_f32_bf16_e32 v25, v13, v243
	v_dot2c_f32_bf16_e32 v22, v14, v244
	v_dot2c_f32_bf16_e32 v24, v15, v245
	s_nop 2
	v_pk_add_f32 v[0:1], v[24:25], v[22:23]
	s_nop 0
	v_add_f32_e32 v0, v0, v1
	s_nop 1
	v_add_f32_dpp v0, v0, v0 quad_perm:[1,0,3,2] row_mask:0xf bank_mask:0xf bound_ctrl:1
	s_nop 1
	v_add_f32_dpp v0, v0, v0 quad_perm:[2,3,0,1] row_mask:0xf bank_mask:0xf bound_ctrl:1
	s_nop 1
	v_add_f32_dpp v0, v0, v0 row_half_mirror row_mask:0xf bank_mask:0xf bound_ctrl:1
	s_nop 1
	v_add_f32_dpp v0, v0, v0 row_mirror row_mask:0xf bank_mask:0xf bound_ctrl:1
	s_waitcnt lgkmcnt(0)
; __device__ __forceinline__ float gelu1(float v) { const f32x2 r = gelu_pk((f32x2){v, v}); return r.x; }
; __device__ __forceinline__ float dot2pb(__bf16 x0, __bf16 x1, unsigned h, float c) { bf2_t x; x[0] = x0; x[1] = x1; bf2_t y; __builtin_memcpy(&y, &h, 4); return __builtin_amdgcn_fdot2_f32_bf16(x, y, c, false); }
; __device__ void ph_peer(const float* __restrict__ SC, const bf16_t* __restrict__ H  , const float* __restrict__ gffn, const unsigned char* __restrict__ U, const unsigned char* __restrict__ V, float* X, const float* __restrict__ fgain) {
;     ...
;             const u32x4* up = (const u32x4*)(U + (size_t)e * 768 + 48 * sub);
;             const u32x4 u0 = up[0], u1 = up[1], u2 = up[2];
;             u32x2 vw[2][3];
; #pragma unroll
;             for (int r = 0; r < 2; ++r) { const int ea = __builtin_amdgcn_readlane(e, 32 * r), eb = __builtin_amdgcn_readlane(e, 32 * r + 16);
;                 const u32x2* vp = (const u32x2*)(V + (size_t)(half ? eb : ea) * 768 + 24 * c32); vw[r][0] = vp[0]; vw[r][1] = vp[1]; vw[r][2] = vp[2]; }
;             float d0 = 0.f, d1 = 0.f, d2 = 0.f, d3 = 0.f;
;             {   const v6u_t p0 = (v6u_t){u0.x, u0.y, u0.z, u0.w, u1.x, u1.y};
;                 const v32bf_t r0 = __builtin_amdgcn_cvt_scalef32_pk32_bf16_fp6(p0, 1.0f);
; #pragma unroll
;                 for (int k = 0; k < 16; k += 4) { d0 = dot2pb(r0[2 * k], r0[2 * k + 1], hf2[k], d0); d1 = dot2pb(r0[2 * k + 2], r0[2 * k + 3], hf2[k + 1], d1);
;                     d2 = dot2pb(r0[2 * k + 4], r0[2 * k + 5], hf2[k + 2], d2); d3 = dot2pb(r0[2 * k + 6], r0[2 * k + 7], hf2[k + 3], d3); } }
;             {   const v6u_t p1 = (v6u_t){u1.z, u1.w, u2.x, u2.y, u2.z, u2.w};
;                 const v32bf_t r1 = __builtin_amdgcn_cvt_scalef32_pk32_bf16_fp6(p1, 1.0f);
; #pragma unroll
;                 for (int k = 0; k < 16; k += 4) { d0 = dot2pb(r1[2 * k], r1[2 * k + 1], hf2[16 + k], d0); d1 = dot2pb(r1[2 * k + 2], r1[2 * k + 3], hf2[16 + k + 1], d1);
;                     d2 = dot2pb(r1[2 * k + 4], r1[2 * k + 5], hf2[16 + k + 2], d2); d3 = dot2pb(r1[2 * k + 6], r1[2 * k + 7], hf2[16 + k + 3], d3); } }
;             const float d = row16_sum((d0 + d1) + (d2 + d3)) * FP6_INV;
;             const float a = gt * gelu1(d) * FP6_INV;
	v_cndmask_b32_e64 v210, v210, v0, s[52:53]
	v_cndmask_b32_e64 v211, v211, v59, s[52:53]
	ds_read_b32 v58, v61 offset:1520
	ds_read_b32 v59, v61 offset:2032
	s_waitcnt lgkmcnt(1)
	v_mad_u32_u24 v0, v58, s14, v92
	global_load_dwordx4 v[44:47], v0, s[46:47]
	global_load_dwordx4 v[48:51], v0, s[46:47] offset:16
	global_load_dwordx4 v[52:55], v0, s[46:47] offset:32
	s_waitcnt vmcnt(4)
	v_cvt_scalef32_pk32_bf16_fp6 v[0:15], v[32:37], 1.0
	v_dot2_f32_bf16 v23, v0, v95, 0
	v_dot2_f32_bf16 v25, v1, v159, 0
	v_dot2_f32_bf16 v22, v2, v160, 0
	v_dot2_f32_bf16 v24, v3, v161, 0
	v_dot2c_f32_bf16_e32 v23, v4, v180
	v_dot2c_f32_bf16_e32 v25, v5, v181
	v_dot2c_f32_bf16_e32 v22, v6, v182
	v_dot2c_f32_bf16_e32 v24, v7, v183
	v_dot2c_f32_bf16_e32 v23, v8, v184
	v_dot2c_f32_bf16_e32 v25, v9, v185
	v_dot2c_f32_bf16_e32 v22, v10, v186
	v_dot2c_f32_bf16_e32 v24, v11, v187
	v_dot2c_f32_bf16_e32 v23, v12, v188
	v_dot2c_f32_bf16_e32 v25, v13, v189
	v_dot2c_f32_bf16_e32 v22, v14, v190
	v_dot2c_f32_bf16_e32 v24, v15, v191
	s_waitcnt vmcnt(3)
	v_cvt_scalef32_pk32_bf16_fp6 v[0:15], v[38:43], 1.0
	v_dot2c_f32_bf16_e32 v23, v0, v192
	v_dot2c_f32_bf16_e32 v25, v1, v193
	v_dot2c_f32_bf16_e32 v22, v2, v194
	v_dot2c_f32_bf16_e32 v24, v3, v195
	v_dot2c_f32_bf16_e32 v23, v4, v196
	v_dot2c_f32_bf16_e32 v25, v5, v197
	v_dot2c_f32_bf16_e32 v22, v6, v198
	v_dot2c_f32_bf16_e32 v24, v7, v199
	v_dot2c_f32_bf16_e32 v23, v8, v200
	v_dot2c_f32_bf16_e32 v25, v9, v201
	v_dot2c_f32_bf16_e32 v22, v10, v202
	v_dot2c_f32_bf16_e32 v24, v11, v203
	v_dot2c_f32_bf16_e32 v23, v12, v204
	v_dot2c_f32_bf16_e32 v25, v13, v205
	v_dot2c_f32_bf16_e32 v22, v14, v206
	v_dot2c_f32_bf16_e32 v24, v15, v207
	s_nop 2
	v_pk_add_f32 v[0:1], v[24:25], v[22:23]
	s_nop 0
	v_add_f32_e32 v0, v0, v1
	s_nop 1
	v_add_f32_dpp v0, v0, v0 quad_perm:[1,0,3,2] row_mask:0xf bank_mask:0xf bound_ctrl:1
	s_nop 1
	v_add_f32_dpp v0, v0, v0 quad_perm:[2,3,0,1] row_mask:0xf bank_mask:0xf bound_ctrl:1
	s_nop 1
	v_add_f32_dpp v0, v0, v0 row_half_mirror row_mask:0xf bank_mask:0xf bound_ctrl:1
	s_nop 1
	v_add_f32_dpp v0, v0, v0 row_mirror row_mask:0xf bank_mask:0xf bound_ctrl:1
	s_waitcnt lgkmcnt(0)
	v_cndmask_b32_e64 v208, v208, v0, s[54:55]
	v_cndmask_b32_e64 v209, v209, v57, s[54:55]
	ds_read_b32 v56, v61
	ds_read_b32 v57, v61 offset:512
	v_add_u32_e32 v61, 16, v61
	s_add_i32 s1, s1, 1
	s_waitcnt lgkmcnt(1)
	v_mad_u32_u24 v0, v56, s14, v92
	global_load_dwordx4 v[32:35], v0, s[46:47]
	global_load_dwordx4 v[36:39], v0, s[46:47] offset:16
	global_load_dwordx4 v[40:43], v0, s[46:47] offset:32
	s_waitcnt vmcnt(4)
	v_cvt_scalef32_pk32_bf16_fp6 v[0:15], v[44:49], 1.0
	v_dot2_f32_bf16 v23, v0, v212, 0
	v_dot2_f32_bf16 v25, v1, v213, 0
	v_dot2_f32_bf16 v22, v2, v214, 0
	v_dot2_f32_bf16 v24, v3, v215, 0
	v_dot2c_f32_bf16_e32 v23, v4, v218
	v_dot2c_f32_bf16_e32 v25, v5, v219
	v_dot2c_f32_bf16_e32 v22, v6, v220
	v_dot2c_f32_bf16_e32 v24, v7, v221
	v_dot2c_f32_bf16_e32 v23, v8, v222
	v_dot2c_f32_bf16_e32 v25, v9, v223
	v_dot2c_f32_bf16_e32 v22, v10, v224
	v_dot2c_f32_bf16_e32 v24, v11, v225
	v_dot2c_f32_bf16_e32 v23, v12, v226
	v_dot2c_f32_bf16_e32 v25, v13, v227
	v_dot2c_f32_bf16_e32 v22, v14, v228
	v_dot2c_f32_bf16_e32 v24, v15, v229
	s_waitcnt vmcnt(3)
	v_cvt_scalef32_pk32_bf16_fp6 v[0:15], v[50:55], 1.0
	v_dot2c_f32_bf16_e32 v23, v0, v230
	v_dot2c_f32_bf16_e32 v25, v1, v231
	v_dot2c_f32_bf16_e32 v22, v2, v232
	v_dot2c_f32_bf16_e32 v24, v3, v233
	v_dot2c_f32_bf16_e32 v23, v4, v234
	v_dot2c_f32_bf16_e32 v25, v5, v235
	v_dot2c_f32_bf16_e32 v22, v6, v236
	v_dot2c_f32_bf16_e32 v24, v7, v237
	v_dot2c_f32_bf16_e32 v23, v8, v238
	v_dot2c_f32_bf16_e32 v25, v9, v239
	v_dot2c_f32_bf16_e32 v22, v10, v240
	v_dot2c_f32_bf16_e32 v24, v11, v241
	v_dot2c_f32_bf16_e32 v23, v12, v242
	v_dot2c_f32_bf16_e32 v25, v13, v243
	v_dot2c_f32_bf16_e32 v22, v14, v244
	v_dot2c_f32_bf16_e32 v24, v15, v245
	s_nop 2
	v_pk_add_f32 v[0:1], v[24:25], v[22:23]
	s_nop 0
	v_add_f32_e32 v0, v0, v1
	s_nop 1
	v_add_f32_dpp v0, v0, v0 quad_perm:[1,0,3,2] row_mask:0xf bank_mask:0xf bound_ctrl:1
	s_nop 1
	v_add_f32_dpp v0, v0, v0 quad_perm:[2,3,0,1] row_mask:0xf bank_mask:0xf bound_ctrl:1
	s_nop 1
	v_add_f32_dpp v0, v0, v0 row_half_mirror row_mask:0xf bank_mask:0xf bound_ctrl:1
	s_nop 1
	v_add_f32_dpp v0, v0, v0 row_mirror row_mask:0xf bank_mask:0xf bound_ctrl:1
	s_waitcnt lgkmcnt(0)
	v_cndmask_b32_e64 v210, v210, v0, s[54:55]
	v_cndmask_b32_e64 v211, v211, v59, s[54:55]
	ds_read_b32 v58, v61 offset:1520
	ds_read_b32 v59, v61 offset:2032
	s_waitcnt lgkmcnt(1)
	v_mad_u32_u24 v0, v58, s14, v92
	global_load_dwordx4 v[44:47], v0, s[46:47]
	global_load_dwordx4 v[48:51], v0, s[46:47] offset:16
	global_load_dwordx4 v[52:55], v0, s[46:47] offset:32
	s_waitcnt vmcnt(4)
	v_cvt_scalef32_pk32_bf16_fp6 v[0:15], v[32:37], 1.0
	v_dot2_f32_bf16 v23, v0, v95, 0
	v_dot2_f32_bf16 v25, v1, v159, 0
	v_dot2_f32_bf16 v22, v2, v160, 0
	v_dot2_f32_bf16 v24, v3, v161, 0
	v_dot2c_f32_bf16_e32 v23, v4, v180
	v_dot2c_f32_bf16_e32 v25, v5, v181
	v_dot2c_f32_bf16_e32 v22, v6, v182
	v_dot2c_f32_bf16_e32 v24, v7, v183
	v_dot2c_f32_bf16_e32 v23, v8, v184
	v_dot2c_f32_bf16_e32 v25, v9, v185
	v_dot2c_f32_bf16_e32 v22, v10, v186
	v_dot2c_f32_bf16_e32 v24, v11, v187
	v_dot2c_f32_bf16_e32 v23, v12, v188
	v_dot2c_f32_bf16_e32 v25, v13, v189
	v_dot2c_f32_bf16_e32 v22, v14, v190
	v_dot2c_f32_bf16_e32 v24, v15, v191
	s_waitcnt vmcnt(3)
; __device__ void ph_peer(const float* __restrict__ SC, const bf16_t* __restrict__ H  , const float* __restrict__ gffn, const unsigned char* __restrict__ U, const unsigned char* __restrict__ V, float* X, const float* __restrict__ fgain) {
;     ...
;             const u32x4* up = (const u32x4*)(U + (size_t)e * 768 + 48 * sub);
;             const u32x4 u0 = up[0], u1 = up[1], u2 = up[2];
;             u32x2 vw[2][3];
; #pragma unroll
;             for (int r = 0; r < 2; ++r) { const int ea = __builtin_amdgcn_readlane(e, 32 * r), eb = __builtin_amdgcn_readlane(e, 32 * r + 16);
;                 const u32x2* vp = (const u32x2*)(V + (size_t)(half ? eb : ea) * 768 + 24 * c32); vw[r][0] = vp[0]; vw[r][1] = vp[1]; vw[r][2] = vp[2]; }
;             float d0 = 0.f, d1 = 0.f, d2 = 0.f, d3 = 0.f;
;             {   const v6u_t p0 = (v6u_t){u0.x, u0.y, u0.z, u0.w, u1.x, u1.y};
;                 const v32bf_t r0 = __builtin_amdgcn_cvt_scalef32_pk32_bf16_fp6(p0, 1.0f);
; #pragma unroll
;                 for (int k = 0; k < 16; k += 4) { d0 = dot2pb(r0[2 * k], r0[2 * k + 1], hf2[k], d0); d1 = dot2pb(r0[2 * k + 2], r0[2 * k + 3], hf2[k + 1], d1);
;                     d2 = dot2pb(r0[2 * k + 4], r0[2 * k + 5], hf2[k + 2], d2); d3 = dot2pb(r0[2 * k + 6], r0[2 * k + 7], hf2[k + 3], d3); } }
;             {   const v6u_t p1 = (v6u_t){u1.z, u1.w, u2.x, u2.y, u2.z, u2.w};
;                 const v32bf_t r1 = __builtin_amdgcn_cvt_scalef32_pk32_bf16_fp6(p1, 1.0f);
; #pragma unroll
;                 for (int k = 0; k < 16; k += 4) { d0 = dot2pb(r1[2 * k], r1[2 * k + 1], hf2[16 + k], d0); d1 = dot2pb(r1[2 * k + 2], r1[2 * k + 3], hf2[16 + k + 1], d1);
;                     d2 = dot2pb(r1[2 * k + 4], r1[2 * k + 5], hf2[16 + k + 2], d2); d3 = dot2pb(r1[2 * k + 6], r1[2 * k + 7], hf2[16 + k + 3], d3); } }
;             const float d = row16_sum((d0 + d1) + (d2 + d3)) * FP6_INV;
;             const float a = gt * gelu1(d) * FP6_INV;
; #pragma unroll
;             for (int r = 0; r < 2; ++r) { const float aa = __int_as_float(__builtin_amdgcn_readlane(__float_as_int(a), 32 * r)), ab = __int_as_float(__builtin_amdgcn_readlane(__float_as_int(a), 32 * r + 16));
;                 const float ak = half ? ab : aa;
;                 const v6u_t pv = (v6u_t){vw[r][0].x, vw[r][0].y, vw[r][1].x, vw[r][1].y, vw[r][2].x, vw[r][2].y};
	v_cvt_scalef32_pk32_bf16_fp6 v[0:15], v[38:43], 1.0
	v_dot2c_f32_bf16_e32 v23, v0, v192
	v_dot2c_f32_bf16_e32 v25, v1, v193
	v_dot2c_f32_bf16_e32 v22, v2, v194
	v_dot2c_f32_bf16_e32 v24, v3, v195
	v_dot2c_f32_bf16_e32 v23, v4, v196
	v_dot2c_f32_bf16_e32 v25, v5, v197
	v_dot2c_f32_bf16_e32 v22, v6, v198
	v_dot2c_f32_bf16_e32 v24, v7, v199
	v_dot2c_f32_bf16_e32 v23, v8, v200
	v_dot2c_f32_bf16_e32 v25, v9, v201
	v_dot2c_f32_bf16_e32 v22, v10, v202
	v_dot2c_f32_bf16_e32 v24, v11, v203
	v_dot2c_f32_bf16_e32 v23, v12, v204
	v_dot2c_f32_bf16_e32 v25, v13, v205
	v_dot2c_f32_bf16_e32 v22, v14, v206
	v_dot2c_f32_bf16_e32 v24, v15, v207
	s_nop 2
	v_pk_add_f32 v[0:1], v[24:25], v[22:23]
	s_nop 0
	v_add_f32_e32 v0, v0, v1
	s_nop 1
	v_add_f32_dpp v0, v0, v0 quad_perm:[1,0,3,2] row_mask:0xf bank_mask:0xf bound_ctrl:1
	s_nop 1
	v_add_f32_dpp v0, v0, v0 quad_perm:[2,3,0,1] row_mask:0xf bank_mask:0xf bound_ctrl:1
	s_nop 1
	v_add_f32_dpp v0, v0, v0 row_half_mirror row_mask:0xf bank_mask:0xf bound_ctrl:1
	s_nop 1
	v_add_f32_dpp v0, v0, v0 row_mirror row_mask:0xf bank_mask:0xf bound_ctrl:1
	s_waitcnt lgkmcnt(0)
	v_cndmask_b32_e64 v0, v208, v0, s[56:57]
	v_cndmask_b32_e64 v209, v209, v57, s[56:57]
	v_mul_f32_e32 v0, 0x3caaaaab, v0
	v_and_b32_e32 v2, 0x7fffffff, v0
	v_pk_fma_f32 v[2:3], v[2:3], s[16:17], 1.0 op_sel_hi:[0,0,0]
	v_rcp_f32_e32 v2, v2
	v_rcp_f32_e32 v3, v3
	v_mul_f32_e32 v1, v0, v0
	v_mul_f32_e32 v1, 0xbf38aa3b, v1
	v_cmp_gt_f32_e32 vcc, 0, v0
	v_pk_fma_f32 v[4:5], v[2:3], s[24:25], v[130:131] op_sel_hi:[1,0,0]
	s_nop 0
	v_pk_fma_f32 v[4:5], v[2:3], v[4:5], s[28:29] op_sel_hi:[1,1,0]
	s_nop 0
	v_pk_fma_f32 v[4:5], v[2:3], v[4:5], s[30:31] op_sel_hi:[1,1,0]
	s_nop 0
	v_pk_fma_f32 v[4:5], v[2:3], v[4:5], s[36:37] op_sel_hi:[1,1,0]
	s_nop 0
	v_pk_mul_f32 v[2:3], v[2:3], v[4:5]
	v_exp_f32_e32 v4, v1
	s_nop 0
	v_pk_mul_f32 v[2:3], v[4:5], v[2:3] op_sel_hi:[0,1]
	v_pk_fma_f32 v[4:5], v[0:1], v[2:3], v[0:1] op_sel_hi:[0,1,1] neg_lo:[1,0,0] neg_hi:[1,0,0]
	v_mul_f32_e32 v0, v0, v2
	v_cndmask_b32_e32 v0, v4, v0, vcc
	v_mul_f32_e32 v0, v0, v209
	v_mul_f32_e32 v60, 0x3caaaaab, v0
	v_add_u32_e32 v62, v61, v155
	ds_write_b32 v62, v60 offset:960
	s_waitcnt vmcnt(1)
	v_cvt_scalef32_pk32_bf16_fp6 v[0:15], v[44:49], 1.0
	v_dot2_f32_bf16 v23, v0, v212, 0
	v_dot2_f32_bf16 v25, v1, v213, 0
	v_dot2_f32_bf16 v22, v2, v214, 0
	v_dot2_f32_bf16 v24, v3, v215, 0
	v_dot2c_f32_bf16_e32 v23, v4, v218
	v_dot2c_f32_bf16_e32 v25, v5, v219
	v_dot2c_f32_bf16_e32 v22, v6, v220
	v_dot2c_f32_bf16_e32 v24, v7, v221
	v_dot2c_f32_bf16_e32 v23, v8, v222
	v_dot2c_f32_bf16_e32 v25, v9, v223
	v_dot2c_f32_bf16_e32 v22, v10, v224
	v_dot2c_f32_bf16_e32 v24, v11, v225
	v_dot2c_f32_bf16_e32 v23, v12, v226
	v_dot2c_f32_bf16_e32 v25, v13, v227
	v_dot2c_f32_bf16_e32 v22, v14, v228
	v_dot2c_f32_bf16_e32 v24, v15, v229
	s_waitcnt vmcnt(0)
	v_cvt_scalef32_pk32_bf16_fp6 v[0:15], v[50:55], 1.0
	v_dot2c_f32_bf16_e32 v23, v0, v230
	v_dot2c_f32_bf16_e32 v25, v1, v231
	v_dot2c_f32_bf16_e32 v22, v2, v232
	v_dot2c_f32_bf16_e32 v24, v3, v233
	v_dot2c_f32_bf16_e32 v23, v4, v234
	v_dot2c_f32_bf16_e32 v25, v5, v235
	v_dot2c_f32_bf16_e32 v22, v6, v236
	v_dot2c_f32_bf16_e32 v24, v7, v237
	v_dot2c_f32_bf16_e32 v23, v8, v238
	v_dot2c_f32_bf16_e32 v25, v9, v239
	v_dot2c_f32_bf16_e32 v22, v10, v240
	v_dot2c_f32_bf16_e32 v24, v11, v241
	v_dot2c_f32_bf16_e32 v23, v12, v242
	v_dot2c_f32_bf16_e32 v25, v13, v243
	v_dot2c_f32_bf16_e32 v22, v14, v244
	v_dot2c_f32_bf16_e32 v24, v15, v245
	s_nop 2
	v_pk_add_f32 v[0:1], v[24:25], v[22:23]
	s_nop 0
	v_add_f32_e32 v0, v0, v1
	s_nop 1
	v_add_f32_dpp v0, v0, v0 quad_perm:[1,0,3,2] row_mask:0xf bank_mask:0xf bound_ctrl:1
	s_nop 1
	v_add_f32_dpp v0, v0, v0 quad_perm:[2,3,0,1] row_mask:0xf bank_mask:0xf bound_ctrl:1
	s_nop 1
	v_add_f32_dpp v0, v0, v0 row_half_mirror row_mask:0xf bank_mask:0xf bound_ctrl:1
	s_nop 1
	v_add_f32_dpp v0, v0, v0 row_mirror row_mask:0xf bank_mask:0xf bound_ctrl:1
	s_waitcnt lgkmcnt(0)
	v_cndmask_b32_e64 v0, v210, v0, s[56:57]
	v_cndmask_b32_e64 v211, v211, v59, s[56:57]
	v_mul_f32_e32 v0, 0x3caaaaab, v0
	v_and_b32_e32 v2, 0x7fffffff, v0
	v_pk_fma_f32 v[2:3], v[2:3], s[16:17], 1.0 op_sel_hi:[0,0,0]
	v_rcp_f32_e32 v2, v2
	v_rcp_f32_e32 v3, v3
	v_mul_f32_e32 v1, v0, v0
	v_mul_f32_e32 v1, 0xbf38aa3b, v1
	v_cmp_gt_f32_e32 vcc, 0, v0
	v_pk_fma_f32 v[4:5], v[2:3], s[24:25], v[130:131] op_sel_hi:[1,0,0]
	s_nop 0
	v_pk_fma_f32 v[4:5], v[2:3], v[4:5], s[28:29] op_sel_hi:[1,1,0]
	s_nop 0
	v_pk_fma_f32 v[4:5], v[2:3], v[4:5], s[30:31] op_sel_hi:[1,1,0]
	s_nop 0
	v_pk_fma_f32 v[4:5], v[2:3], v[4:5], s[36:37] op_sel_hi:[1,1,0]
	s_nop 0
	v_pk_mul_f32 v[2:3], v[2:3], v[4:5]
	v_exp_f32_e32 v4, v1
	s_nop 0
	v_pk_mul_f32 v[2:3], v[4:5], v[2:3] op_sel_hi:[0,1]
	v_pk_fma_f32 v[4:5], v[0:1], v[2:3], v[0:1] op_sel_hi:[0,1,1] neg_lo:[1,0,0] neg_hi:[1,0,0]
	v_mul_f32_e32 v0, v0, v2
	v_cndmask_b32_e32 v0, v4, v0, vcc
	v_mul_f32_e32 v0, v0, v211
	v_mul_f32_e32 v60, 0x3caaaaab, v0
	v_add_u32_e32 v62, v61, v155
	ds_write_b32 v62, v60 offset:2496
	v_mov_b32_e32 v180, 0
	v_mov_b32_e32 v181, 0
	v_mov_b32_e32 v182, 0
	v_mov_b32_e32 v183, 0
	v_mov_b32_e32 v184, 0
	v_mov_b32_e32 v185, 0
	v_mov_b32_e32 v186, 0
	v_mov_b32_e32 v187, 0
	v_mov_b32_e32 v188, 0
	v_mov_b32_e32 v189, 0
	v_mov_b32_e32 v190, 0
	v_mov_b32_e32 v191, 0
	v_mov_b32_e32 v192, 0
	v_mov_b32_e32 v193, 0
	v_mov_b32_e32 v194, 0
	v_mov_b32_e32 v195, 0
	v_mov_b32_e32 v196, 0
	v_mov_b32_e32 v197, 0
	v_mov_b32_e32 v198, 0
	v_mov_b32_e32 v199, 0
	v_mov_b32_e32 v200, 0
	v_mov_b32_e32 v201, 0
	v_mov_b32_e32 v202, 0
	v_mov_b32_e32 v203, 0
	v_mov_b32_e32 v204, 0
	v_mov_b32_e32 v205, 0
	v_mov_b32_e32 v206, 0
	v_mov_b32_e32 v207, 0
	v_mov_b32_e32 v208, 0
	v_mov_b32_e32 v209, 0
	v_mov_b32_e32 v210, 0
	v_mov_b32_e32 v211, 0
	s_barrier
	v_lshrrev_b32_e32 v61, 6, v131
	v_lshrrev_b32_e32 v0, 5, v74
	v_mul_u32_u24_e32 v61, 0x2400, v61
	v_lshl_add_u32 v61, v0, 2, v61
	s_mov_b32 s1, 0
	ds_read_b32 v32, v61 offset:0
	ds_read_b32 v33, v61 offset:8
	ds_read_b32 v56, v61 offset:1024
	ds_read_b32 v58, v61 offset:1032
	v_add_u32_e32 v61, 16, v61
	s_add_i32 s1, s1, 1
	s_waitcnt lgkmcnt(2)
	v_mad_u32_u24 v0, v32, s14, v93
	v_mad_u32_u24 v1, v33, s14, v93
	global_load_dwordx4 v[44:47], v0, s[48:49]
	global_load_dwordx2 v[48:49], v0, s[48:49] offset:16
	global_load_dwordx4 v[50:53], v1, s[48:49]
	global_load_dwordx2 v[54:55], v1, s[48:49] offset:16
; __device__ void ph_peer(const float* __restrict__ SC, const bf16_t* __restrict__ H  , const float* __restrict__ gffn, const unsigned char* __restrict__ U, const unsigned char* __restrict__ V, float* X, const float* __restrict__ fgain) {
;     ...
;             const u32x4* up = (const u32x4*)(U + (size_t)e * 768 + 48 * sub);
;             const u32x4 u0 = up[0], u1 = up[1], u2 = up[2];
;             u32x2 vw[2][3];
; #pragma unroll
;             for (int r = 0; r < 2; ++r) { const int ea = __builtin_amdgcn_readlane(e, 32 * r), eb = __builtin_amdgcn_readlane(e, 32 * r + 16);
;                 const u32x2* vp = (const u32x2*)(V + (size_t)(half ? eb : ea) * 768 + 24 * c32); vw[r][0] = vp[0]; vw[r][1] = vp[1]; vw[r][2] = vp[2]; }
;             float d0 = 0.f, d1 = 0.f, d2 = 0.f, d3 = 0.f;
;             {   const v6u_t p0 = (v6u_t){u0.x, u0.y, u0.z, u0.w, u1.x, u1.y};
;                 const v32bf_t r0 = __builtin_amdgcn_cvt_scalef32_pk32_bf16_fp6(p0, 1.0f);
; #pragma unroll
;                 for (int k = 0; k < 16; k += 4) { d0 = dot2pb(r0[2 * k], r0[2 * k + 1], hf2[k], d0); d1 = dot2pb(r0[2 * k + 2], r0[2 * k + 3], hf2[k + 1], d1);
;                     d2 = dot2pb(r0[2 * k + 4], r0[2 * k + 5], hf2[k + 2], d2); d3 = dot2pb(r0[2 * k + 6], r0[2 * k + 7], hf2[k + 3], d3); } }
;             {   const v6u_t p1 = (v6u_t){u1.z, u1.w, u2.x, u2.y, u2.z, u2.w};
;                 const v32bf_t r1 = __builtin_amdgcn_cvt_scalef32_pk32_bf16_fp6(p1, 1.0f);
; #pragma unroll
;                 for (int k = 0; k < 16; k += 4) { d0 = dot2pb(r1[2 * k], r1[2 * k + 1], hf2[16 + k], d0); d1 = dot2pb(r1[2 * k + 2], r1[2 * k + 3], hf2[16 + k + 1], d1);
;                     d2 = dot2pb(r1[2 * k + 4], r1[2 * k + 5], hf2[16 + k + 2], d2); d3 = dot2pb(r1[2 * k + 6], r1[2 * k + 7], hf2[16 + k + 3], d3); } }
;             const float d = row16_sum((d0 + d1) + (d2 + d3)) * FP6_INV;
;             const float a = gt * gelu1(d) * FP6_INV;
; #pragma unroll
;             for (int r = 0; r < 2; ++r) { const float aa = __int_as_float(__builtin_amdgcn_readlane(__float_as_int(a), 32 * r)), ab = __int_as_float(__builtin_amdgcn_readlane(__float_as_int(a), 32 * r + 16));
;                 const float ak = half ? ab : aa;
;                 const v6u_t pv = (v6u_t){vw[r][0].x, vw[r][0].y, vw[r][1].x, vw[r][1].y, vw[r][2].x, vw[r][2].y};
.Lpeer_vloop:
	ds_read_b32 v218, v61 offset:1520
	ds_read_b32 v219, v61 offset:1528
	ds_read_b32 v220, v61 offset:2544
	ds_read_b32 v222, v61 offset:2552
	s_waitcnt lgkmcnt(2)
	v_mad_u32_u24 v0, v218, s14, v93
	v_mad_u32_u24 v1, v219, s14, v93
	global_load_dwordx4 v[230:233], v0, s[48:49]
	global_load_dwordx2 v[234:235], v0, s[48:49] offset:16
	global_load_dwordx4 v[236:239], v1, s[48:49]
	global_load_dwordx2 v[240:241], v1, s[48:49] offset:16
	s_waitcnt vmcnt(6)
	v_cvt_scalef32_pk32_f32_fp6 v[0:31], v[44:49], 1.0
	v_pk_fma_f32 v[126:127], v[0:1], v[56:57], v[126:127] op_sel_hi:[1,0,1]
	v_pk_fma_f32 v[122:123], v[2:3], v[56:57], v[122:123] op_sel_hi:[1,0,1]
	v_pk_fma_f32 v[114:115], v[4:5], v[56:57], v[114:115] op_sel_hi:[1,0,1]
	v_pk_fma_f32 v[116:117], v[6:7], v[56:57], v[116:117] op_sel_hi:[1,0,1]
	v_pk_fma_f32 v[106:107], v[8:9], v[56:57], v[106:107] op_sel_hi:[1,0,1]
	v_pk_fma_f32 v[108:109], v[10:11], v[56:57], v[108:109] op_sel_hi:[1,0,1]
	v_pk_fma_f32 v[98:99], v[12:13], v[56:57], v[98:99] op_sel_hi:[1,0,1]
	v_pk_fma_f32 v[100:101], v[14:15], v[56:57], v[100:101] op_sel_hi:[1,0,1]
	v_pk_fma_f32 v[144:145], v[16:17], v[56:57], v[144:145] op_sel_hi:[1,0,1]
	v_pk_fma_f32 v[124:125], v[18:19], v[56:57], v[124:125] op_sel_hi:[1,0,1]
	v_pk_fma_f32 v[118:119], v[20:21], v[56:57], v[118:119] op_sel_hi:[1,0,1]
	v_pk_fma_f32 v[120:121], v[22:23], v[56:57], v[120:121] op_sel_hi:[1,0,1]
	v_pk_fma_f32 v[110:111], v[24:25], v[56:57], v[110:111] op_sel_hi:[1,0,1]
	v_pk_fma_f32 v[112:113], v[26:27], v[56:57], v[112:113] op_sel_hi:[1,0,1]
	v_pk_fma_f32 v[102:103], v[28:29], v[56:57], v[102:103] op_sel_hi:[1,0,1]
	v_pk_fma_f32 v[104:105], v[30:31], v[56:57], v[104:105] op_sel_hi:[1,0,1]
	s_waitcnt vmcnt(4)
	v_cvt_scalef32_pk32_f32_fp6 v[0:31], v[50:55], 1.0
	v_pk_fma_f32 v[126:127], v[0:1], v[58:59], v[126:127] op_sel_hi:[1,0,1]
	v_pk_fma_f32 v[122:123], v[2:3], v[58:59], v[122:123] op_sel_hi:[1,0,1]
	v_pk_fma_f32 v[114:115], v[4:5], v[58:59], v[114:115] op_sel_hi:[1,0,1]
	v_pk_fma_f32 v[116:117], v[6:7], v[58:59], v[116:117] op_sel_hi:[1,0,1]
	v_pk_fma_f32 v[106:107], v[8:9], v[58:59], v[106:107] op_sel_hi:[1,0,1]
	v_pk_fma_f32 v[108:109], v[10:11], v[58:59], v[108:109] op_sel_hi:[1,0,1]
	v_pk_fma_f32 v[98:99], v[12:13], v[58:59], v[98:99] op_sel_hi:[1,0,1]
	v_pk_fma_f32 v[100:101], v[14:15], v[58:59], v[100:101] op_sel_hi:[1,0,1]
	v_pk_fma_f32 v[144:145], v[16:17], v[58:59], v[144:145] op_sel_hi:[1,0,1]
	v_pk_fma_f32 v[124:125], v[18:19], v[58:59], v[124:125] op_sel_hi:[1,0,1]
	v_pk_fma_f32 v[118:119], v[20:21], v[58:59], v[118:119] op_sel_hi:[1,0,1]
	v_pk_fma_f32 v[120:121], v[22:23], v[58:59], v[120:121] op_sel_hi:[1,0,1]
	v_pk_fma_f32 v[110:111], v[24:25], v[58:59], v[110:111] op_sel_hi:[1,0,1]
	v_pk_fma_f32 v[112:113], v[26:27], v[58:59], v[112:113] op_sel_hi:[1,0,1]
	v_pk_fma_f32 v[102:103], v[28:29], v[58:59], v[102:103] op_sel_hi:[1,0,1]
	v_pk_fma_f32 v[104:105], v[30:31], v[58:59], v[104:105] op_sel_hi:[1,0,1]
	ds_read_b32 v32, v61 offset:0
	ds_read_b32 v33, v61 offset:8
	ds_read_b32 v56, v61 offset:1024
	ds_read_b32 v58, v61 offset:1032
	v_add_u32_e32 v61, 16, v61
	s_add_i32 s1, s1, 1
	s_waitcnt lgkmcnt(2)
	v_mad_u32_u24 v0, v32, s14, v93
	v_mad_u32_u24 v1, v33, s14, v93
	global_load_dwordx4 v[44:47], v0, s[48:49]
	global_load_dwordx2 v[48:49], v0, s[48:49] offset:16
	global_load_dwordx4 v[50:53], v1, s[48:49]
	global_load_dwordx2 v[54:55], v1, s[48:49] offset:16
	s_waitcnt vmcnt(6)
	v_cvt_scalef32_pk32_f32_fp6 v[0:31], v[230:235], 1.0
	v_pk_fma_f32 v[180:181], v[0:1], v[220:221], v[180:181] op_sel_hi:[1,0,1]
	v_pk_fma_f32 v[182:183], v[2:3], v[220:221], v[182:183] op_sel_hi:[1,0,1]
	v_pk_fma_f32 v[184:185], v[4:5], v[220:221], v[184:185] op_sel_hi:[1,0,1]
	v_pk_fma_f32 v[186:187], v[6:7], v[220:221], v[186:187] op_sel_hi:[1,0,1]
	v_pk_fma_f32 v[188:189], v[8:9], v[220:221], v[188:189] op_sel_hi:[1,0,1]
	v_pk_fma_f32 v[190:191], v[10:11], v[220:221], v[190:191] op_sel_hi:[1,0,1]
	v_pk_fma_f32 v[192:193], v[12:13], v[220:221], v[192:193] op_sel_hi:[1,0,1]
	v_pk_fma_f32 v[194:195], v[14:15], v[220:221], v[194:195] op_sel_hi:[1,0,1]
	v_pk_fma_f32 v[196:197], v[16:17], v[220:221], v[196:197] op_sel_hi:[1,0,1]
	v_pk_fma_f32 v[198:199], v[18:19], v[220:221], v[198:199] op_sel_hi:[1,0,1]
	v_pk_fma_f32 v[200:201], v[20:21], v[220:221], v[200:201] op_sel_hi:[1,0,1]
	v_pk_fma_f32 v[202:203], v[22:23], v[220:221], v[202:203] op_sel_hi:[1,0,1]
	v_pk_fma_f32 v[204:205], v[24:25], v[220:221], v[204:205] op_sel_hi:[1,0,1]
	v_pk_fma_f32 v[206:207], v[26:27], v[220:221], v[206:207] op_sel_hi:[1,0,1]
	v_pk_fma_f32 v[208:209], v[28:29], v[220:221], v[208:209] op_sel_hi:[1,0,1]
	v_pk_fma_f32 v[210:211], v[30:31], v[220:221], v[210:211] op_sel_hi:[1,0,1]
	s_waitcnt vmcnt(4)
	v_cvt_scalef32_pk32_f32_fp6 v[0:31], v[236:241], 1.0
	v_pk_fma_f32 v[180:181], v[0:1], v[222:223], v[180:181] op_sel_hi:[1,0,1]
	v_pk_fma_f32 v[182:183], v[2:3], v[222:223], v[182:183] op_sel_hi:[1,0,1]
	v_pk_fma_f32 v[184:185], v[4:5], v[222:223], v[184:185] op_sel_hi:[1,0,1]
	v_pk_fma_f32 v[186:187], v[6:7], v[222:223], v[186:187] op_sel_hi:[1,0,1]
	v_pk_fma_f32 v[188:189], v[8:9], v[222:223], v[188:189] op_sel_hi:[1,0,1]
	v_pk_fma_f32 v[190:191], v[10:11], v[222:223], v[190:191] op_sel_hi:[1,0,1]
	v_pk_fma_f32 v[192:193], v[12:13], v[222:223], v[192:193] op_sel_hi:[1,0,1]
	v_pk_fma_f32 v[194:195], v[14:15], v[222:223], v[194:195] op_sel_hi:[1,0,1]
	v_pk_fma_f32 v[196:197], v[16:17], v[222:223], v[196:197] op_sel_hi:[1,0,1]
	v_pk_fma_f32 v[198:199], v[18:19], v[222:223], v[198:199] op_sel_hi:[1,0,1]
	v_pk_fma_f32 v[200:201], v[20:21], v[222:223], v[200:201] op_sel_hi:[1,0,1]
	v_pk_fma_f32 v[202:203], v[22:23], v[222:223], v[202:203] op_sel_hi:[1,0,1]
	v_pk_fma_f32 v[204:205], v[24:25], v[222:223], v[204:205] op_sel_hi:[1,0,1]
	v_pk_fma_f32 v[206:207], v[26:27], v[222:223], v[206:207] op_sel_hi:[1,0,1]
	v_pk_fma_f32 v[208:209], v[28:29], v[222:223], v[208:209] op_sel_hi:[1,0,1]
	v_pk_fma_f32 v[210:211], v[30:31], v[222:223], v[210:211] op_sel_hi:[1,0,1]
	s_cmp_lt_u32 s1, 32
	s_cbranch_scc1 .Lpeer_vloop
; __device__ void ph_peer(const float* __restrict__ SC, const bf16_t* __restrict__ H  , const float* __restrict__ gffn, const unsigned char* __restrict__ U, const unsigned char* __restrict__ V, float* X, const float* __restrict__ fgain) {
;     ...
; #pragma unroll
;             for (int r = 0; r < 2; ++r) { const float aa = __int_as_float(__builtin_amdgcn_readlane(__float_as_int(a), 32 * r)), ab = __int_as_float(__builtin_amdgcn_readlane(__float_as_int(a), 32 * r + 16));
;                 const float ak = half ? ab : aa;
;                 const v6u_t pv = (v6u_t){vw[r][0].x, vw[r][0].y, vw[r][1].x, vw[r][1].y, vw[r][2].x, vw[r][2].y};
;                 const v32f_t rv = __builtin_amdgcn_cvt_scalef32_pk32_f32_fp6(pv, 1.0f);
; #pragma unroll
;                 for (int i = 0; i < 32; ++i) acc[i] += ak * rv[i]; }
;         }
;         __builtin_amdgcn_s_setprio(0);
;         float o16[16];
; #pragma unroll
;         for (int i = 0; i < 16; ++i) { const float lo = acc[i] + __shfl_xor(acc[i], 32), hi = acc[16 + i] + __shfl_xor(acc[16 + i], 32); o16[i] = half ? hi : lo; }
	ds_read_b32 v218, v61 offset:1520
	ds_read_b32 v219, v61 offset:1528
	ds_read_b32 v220, v61 offset:2544
	ds_read_b32 v222, v61 offset:2552
	s_waitcnt lgkmcnt(2)
	v_mad_u32_u24 v0, v218, s14, v93
	v_mad_u32_u24 v1, v219, s14, v93
	global_load_dwordx4 v[230:233], v0, s[48:49]
	global_load_dwordx2 v[234:235], v0, s[48:49] offset:16
	global_load_dwordx4 v[236:239], v1, s[48:49]
	global_load_dwordx2 v[240:241], v1, s[48:49] offset:16
	s_waitcnt vmcnt(6)
	v_cvt_scalef32_pk32_f32_fp6 v[0:31], v[44:49], 1.0
	v_pk_fma_f32 v[126:127], v[0:1], v[56:57], v[126:127] op_sel_hi:[1,0,1]
	v_pk_fma_f32 v[122:123], v[2:3], v[56:57], v[122:123] op_sel_hi:[1,0,1]
	v_pk_fma_f32 v[114:115], v[4:5], v[56:57], v[114:115] op_sel_hi:[1,0,1]
	v_pk_fma_f32 v[116:117], v[6:7], v[56:57], v[116:117] op_sel_hi:[1,0,1]
	v_pk_fma_f32 v[106:107], v[8:9], v[56:57], v[106:107] op_sel_hi:[1,0,1]
	v_pk_fma_f32 v[108:109], v[10:11], v[56:57], v[108:109] op_sel_hi:[1,0,1]
	v_pk_fma_f32 v[98:99], v[12:13], v[56:57], v[98:99] op_sel_hi:[1,0,1]
	v_pk_fma_f32 v[100:101], v[14:15], v[56:57], v[100:101] op_sel_hi:[1,0,1]
	v_pk_fma_f32 v[144:145], v[16:17], v[56:57], v[144:145] op_sel_hi:[1,0,1]
	v_pk_fma_f32 v[124:125], v[18:19], v[56:57], v[124:125] op_sel_hi:[1,0,1]
	v_pk_fma_f32 v[118:119], v[20:21], v[56:57], v[118:119] op_sel_hi:[1,0,1]
	v_pk_fma_f32 v[120:121], v[22:23], v[56:57], v[120:121] op_sel_hi:[1,0,1]
	v_pk_fma_f32 v[110:111], v[24:25], v[56:57], v[110:111] op_sel_hi:[1,0,1]
	v_pk_fma_f32 v[112:113], v[26:27], v[56:57], v[112:113] op_sel_hi:[1,0,1]
	v_pk_fma_f32 v[102:103], v[28:29], v[56:57], v[102:103] op_sel_hi:[1,0,1]
	v_pk_fma_f32 v[104:105], v[30:31], v[56:57], v[104:105] op_sel_hi:[1,0,1]
	s_waitcnt vmcnt(4)
	v_cvt_scalef32_pk32_f32_fp6 v[0:31], v[50:55], 1.0
	v_pk_fma_f32 v[126:127], v[0:1], v[58:59], v[126:127] op_sel_hi:[1,0,1]
	v_pk_fma_f32 v[122:123], v[2:3], v[58:59], v[122:123] op_sel_hi:[1,0,1]
	v_pk_fma_f32 v[114:115], v[4:5], v[58:59], v[114:115] op_sel_hi:[1,0,1]
	v_pk_fma_f32 v[116:117], v[6:7], v[58:59], v[116:117] op_sel_hi:[1,0,1]
	v_pk_fma_f32 v[106:107], v[8:9], v[58:59], v[106:107] op_sel_hi:[1,0,1]
	v_pk_fma_f32 v[108:109], v[10:11], v[58:59], v[108:109] op_sel_hi:[1,0,1]
	v_pk_fma_f32 v[98:99], v[12:13], v[58:59], v[98:99] op_sel_hi:[1,0,1]
	v_pk_fma_f32 v[100:101], v[14:15], v[58:59], v[100:101] op_sel_hi:[1,0,1]
	v_pk_fma_f32 v[144:145], v[16:17], v[58:59], v[144:145] op_sel_hi:[1,0,1]
	v_pk_fma_f32 v[124:125], v[18:19], v[58:59], v[124:125] op_sel_hi:[1,0,1]
	v_pk_fma_f32 v[118:119], v[20:21], v[58:59], v[118:119] op_sel_hi:[1,0,1]
	v_pk_fma_f32 v[120:121], v[22:23], v[58:59], v[120:121] op_sel_hi:[1,0,1]
	v_pk_fma_f32 v[110:111], v[24:25], v[58:59], v[110:111] op_sel_hi:[1,0,1]
	v_pk_fma_f32 v[112:113], v[26:27], v[58:59], v[112:113] op_sel_hi:[1,0,1]
	v_pk_fma_f32 v[102:103], v[28:29], v[58:59], v[102:103] op_sel_hi:[1,0,1]
	v_pk_fma_f32 v[104:105], v[30:31], v[58:59], v[104:105] op_sel_hi:[1,0,1]
	s_waitcnt vmcnt(2) lgkmcnt(0)
	v_cvt_scalef32_pk32_f32_fp6 v[0:31], v[230:235], 1.0
	v_pk_fma_f32 v[180:181], v[0:1], v[220:221], v[180:181] op_sel_hi:[1,0,1]
	v_pk_fma_f32 v[182:183], v[2:3], v[220:221], v[182:183] op_sel_hi:[1,0,1]
	v_pk_fma_f32 v[184:185], v[4:5], v[220:221], v[184:185] op_sel_hi:[1,0,1]
	v_pk_fma_f32 v[186:187], v[6:7], v[220:221], v[186:187] op_sel_hi:[1,0,1]
	v_pk_fma_f32 v[188:189], v[8:9], v[220:221], v[188:189] op_sel_hi:[1,0,1]
	v_pk_fma_f32 v[190:191], v[10:11], v[220:221], v[190:191] op_sel_hi:[1,0,1]
	v_pk_fma_f32 v[192:193], v[12:13], v[220:221], v[192:193] op_sel_hi:[1,0,1]
	v_pk_fma_f32 v[194:195], v[14:15], v[220:221], v[194:195] op_sel_hi:[1,0,1]
	v_pk_fma_f32 v[196:197], v[16:17], v[220:221], v[196:197] op_sel_hi:[1,0,1]
	v_pk_fma_f32 v[198:199], v[18:19], v[220:221], v[198:199] op_sel_hi:[1,0,1]
	v_pk_fma_f32 v[200:201], v[20:21], v[220:221], v[200:201] op_sel_hi:[1,0,1]
	v_pk_fma_f32 v[202:203], v[22:23], v[220:221], v[202:203] op_sel_hi:[1,0,1]
	v_pk_fma_f32 v[204:205], v[24:25], v[220:221], v[204:205] op_sel_hi:[1,0,1]
	v_pk_fma_f32 v[206:207], v[26:27], v[220:221], v[206:207] op_sel_hi:[1,0,1]
	v_pk_fma_f32 v[208:209], v[28:29], v[220:221], v[208:209] op_sel_hi:[1,0,1]
	v_pk_fma_f32 v[210:211], v[30:31], v[220:221], v[210:211] op_sel_hi:[1,0,1]
	s_waitcnt vmcnt(0)
	v_cvt_scalef32_pk32_f32_fp6 v[0:31], v[236:241], 1.0
	v_pk_fma_f32 v[180:181], v[0:1], v[222:223], v[180:181] op_sel_hi:[1,0,1]
	v_pk_fma_f32 v[182:183], v[2:3], v[222:223], v[182:183] op_sel_hi:[1,0,1]
	v_pk_fma_f32 v[184:185], v[4:5], v[222:223], v[184:185] op_sel_hi:[1,0,1]
	v_pk_fma_f32 v[186:187], v[6:7], v[222:223], v[186:187] op_sel_hi:[1,0,1]
	v_pk_fma_f32 v[188:189], v[8:9], v[222:223], v[188:189] op_sel_hi:[1,0,1]
	v_pk_fma_f32 v[190:191], v[10:11], v[222:223], v[190:191] op_sel_hi:[1,0,1]
	v_pk_fma_f32 v[192:193], v[12:13], v[222:223], v[192:193] op_sel_hi:[1,0,1]
	v_pk_fma_f32 v[194:195], v[14:15], v[222:223], v[194:195] op_sel_hi:[1,0,1]
	v_pk_fma_f32 v[196:197], v[16:17], v[222:223], v[196:197] op_sel_hi:[1,0,1]
	v_pk_fma_f32 v[198:199], v[18:19], v[222:223], v[198:199] op_sel_hi:[1,0,1]
	v_pk_fma_f32 v[200:201], v[20:21], v[222:223], v[200:201] op_sel_hi:[1,0,1]
	v_pk_fma_f32 v[202:203], v[22:23], v[222:223], v[202:203] op_sel_hi:[1,0,1]
	v_pk_fma_f32 v[204:205], v[24:25], v[222:223], v[204:205] op_sel_hi:[1,0,1]
	v_pk_fma_f32 v[206:207], v[26:27], v[222:223], v[206:207] op_sel_hi:[1,0,1]
	v_pk_fma_f32 v[208:209], v[28:29], v[222:223], v[208:209] op_sel_hi:[1,0,1]
	v_pk_fma_f32 v[210:211], v[30:31], v[222:223], v[210:211] op_sel_hi:[1,0,1]
	s_setprio 0
	ds_bpermute_b32 v0, v154, v126
	ds_bpermute_b32 v2, v154, v144
	ds_bpermute_b32 v1, v154, v127
	ds_bpermute_b32 v3, v154, v145
	v_lshl_add_u64 v[28:29], v[96:97], 2, v[84:85]
	ds_bpermute_b32 v16, v154, v122
	ds_bpermute_b32 v18, v154, v124
	s_waitcnt lgkmcnt(3)
; __device__ void ph_peer(const float* __restrict__ SC, const bf16_t* __restrict__ H  , const float* __restrict__ gffn, const unsigned char* __restrict__ U, const unsigned char* __restrict__ V, float* X, const float* __restrict__ fgain) {
;     ...
;         for (int i = 0; i < 16; ++i) { const float lo = acc[i] + __shfl_xor(acc[i], 32), hi = acc[16 + i] + __shfl_xor(acc[16 + i], 32); o16[i] = half ? hi : lo; }
;         float4* xp = (float4*)(X + (size_t)tok * 1024 + 32 * c32 + 16 * half);
;         float4 xo[4]; float ss = 0.f;
; #pragma unroll
;         for (int j = 0; j < 4; ++j) { float4 a = xp[j]; a.x += o16[j * 4 + 0]; a.y += o16[j * 4 + 1]; a.z += o16[j * 4 + 2]; a.w += o16[j * 4 + 3]; xo[j] = a; ss += a.x * a.x + a.y * a.y + a.z * a.z + a.w * a.w; }
;         if (fgain) { ss = wave_sum(ss); const float rs = rsqrtf(ss * (1.0f / 1024.0f) + 1e-6f);
; #pragma unroll
;             for (int j = 0; j < 4; ++j) { const float4 g = *(const float4*)(fgain + 32 * c32 + 16 * half + j * 4); xo[j].x *= rs * g.x; xo[j].y *= rs * g.y; xo[j].z *= rs * g.z; xo[j].w *= rs * g.w; } }
; #pragma unroll
;         for (int j = 0; j < 4; ++j) xp[j] = xo[j];
	v_pk_add_f32 v[0:1], v[126:127], v[0:1]
	s_waitcnt lgkmcnt(2)
	v_pk_add_f32 v[2:3], v[144:145], v[2:3]
	ds_bpermute_b32 v17, v154, v123
	v_cndmask_b32_e64 v47, v3, v1, s[44:45]
	v_cndmask_b32_e64 v46, v2, v0, s[44:45]
	global_load_dwordx4 v[8:11], v[28:29], off offset:48
	global_load_dwordx4 v[12:15], v[28:29], off offset:32
	global_load_dwordx4 v[4:7], v[28:29], off offset:16
	global_load_dwordx4 v[0:3], v[28:29], off
	ds_bpermute_b32 v19, v154, v125
	ds_bpermute_b32 v20, v154, v114
	ds_bpermute_b32 v22, v154, v118
	ds_bpermute_b32 v21, v154, v115
	ds_bpermute_b32 v23, v154, v119
	ds_bpermute_b32 v24, v154, v116
	ds_bpermute_b32 v26, v154, v120
	ds_bpermute_b32 v25, v154, v117
	ds_bpermute_b32 v27, v154, v121
	ds_bpermute_b32 v30, v154, v106
	ds_bpermute_b32 v32, v154, v110
	ds_bpermute_b32 v31, v154, v107
	ds_bpermute_b32 v33, v154, v111
	s_waitcnt lgkmcnt(13)
	v_pk_add_f32 v[16:17], v[122:123], v[16:17]
	s_waitcnt lgkmcnt(12)
	v_pk_add_f32 v[18:19], v[124:125], v[18:19]
	ds_bpermute_b32 v34, v154, v108
	ds_bpermute_b32 v36, v154, v112
	ds_bpermute_b32 v35, v154, v109
	ds_bpermute_b32 v37, v154, v113
	v_cndmask_b32_e64 v17, v19, v17, s[44:45]
	v_cndmask_b32_e64 v16, v18, v16, s[44:45]
	s_waitcnt lgkmcnt(12)
	v_pk_add_f32 v[18:19], v[118:119], v[22:23]
	ds_bpermute_b32 v38, v154, v98
	ds_bpermute_b32 v40, v154, v102
	ds_bpermute_b32 v39, v154, v99
	ds_bpermute_b32 v41, v154, v103
	ds_bpermute_b32 v42, v154, v100
	ds_bpermute_b32 v44, v154, v104
	ds_bpermute_b32 v43, v154, v101
	ds_bpermute_b32 v45, v154, v105
	s_and_b64 vcc, exec, s[92:93]
	s_waitcnt vmcnt(0)
	v_pk_add_f32 v[2:3], v[16:17], v[2:3]
	v_pk_add_f32 v[16:17], v[114:115], v[20:21]
	s_waitcnt lgkmcnt(14)
	v_pk_add_f32 v[20:21], v[120:121], v[26:27]
	v_cndmask_b32_e64 v17, v19, v17, s[44:45]
	v_cndmask_b32_e64 v16, v18, v16, s[44:45]
	v_pk_add_f32 v[18:19], v[116:117], v[24:25]
	v_pk_add_f32 v[4:5], v[16:17], v[4:5]
	v_cndmask_b32_e64 v19, v21, v19, s[44:45]
	v_cndmask_b32_e64 v18, v20, v18, s[44:45]
	v_pk_add_f32 v[6:7], v[18:19], v[6:7]
	s_waitcnt lgkmcnt(13)
	v_pk_add_f32 v[16:17], v[106:107], v[30:31]
	s_waitcnt lgkmcnt(12)
	v_pk_add_f32 v[18:19], v[110:111], v[32:33]
	s_waitcnt lgkmcnt(8)
	v_pk_add_f32 v[20:21], v[112:113], v[36:37]
	v_cndmask_b32_e64 v17, v19, v17, s[44:45]
	v_cndmask_b32_e64 v16, v18, v16, s[44:45]
	v_pk_add_f32 v[18:19], v[108:109], v[34:35]
	v_pk_add_f32 v[12:13], v[16:17], v[12:13]
	v_cndmask_b32_e64 v19, v21, v19, s[44:45]
	v_cndmask_b32_e64 v18, v20, v18, s[44:45]
	v_pk_add_f32 v[14:15], v[18:19], v[14:15]
	s_waitcnt lgkmcnt(5)
	v_pk_add_f32 v[16:17], v[98:99], v[38:39]
	s_waitcnt lgkmcnt(4)
	v_pk_add_f32 v[18:19], v[102:103], v[40:41]
	s_waitcnt lgkmcnt(0)
	v_pk_add_f32 v[20:21], v[104:105], v[44:45]
	v_cndmask_b32_e64 v17, v19, v17, s[44:45]
	v_cndmask_b32_e64 v16, v18, v16, s[44:45]
	v_pk_add_f32 v[18:19], v[100:101], v[42:43]
	v_pk_add_f32 v[0:1], v[46:47], v[0:1]
	v_cndmask_b32_e64 v19, v21, v19, s[44:45]
	v_cndmask_b32_e64 v18, v20, v18, s[44:45]
	v_pk_add_f32 v[8:9], v[16:17], v[8:9]
	v_pk_add_f32 v[10:11], v[18:19], v[10:11]
	s_cbranch_vccz .Lpeer_st_a
	v_mov_b32_e32 v18, v1
	v_mov_b32_e32 v19, v5
	v_mov_b32_e32 v16, v0
	v_mov_b32_e32 v17, v4
	v_pk_mul_f32 v[18:19], v[18:19], v[18:19]
	v_mov_b32_e32 v20, v13
	v_pk_fma_f32 v[16:17], v[16:17], v[16:17], v[18:19]
	v_mov_b32_e32 v18, v2
	v_mov_b32_e32 v19, v6
	v_pk_fma_f32 v[16:17], v[18:19], v[18:19], v[16:17]
	v_mov_b32_e32 v18, v3
	v_mov_b32_e32 v19, v7
	v_mov_b32_e32 v21, v9
	v_pk_fma_f32 v[16:17], v[18:19], v[18:19], v[16:17]
	v_mov_b32_e32 v18, v12
	v_mov_b32_e32 v19, v8
	v_pk_mul_f32 v[20:21], v[20:21], v[20:21]
	v_add_f32_e32 v16, v16, v17
	v_pk_fma_f32 v[18:19], v[18:19], v[18:19], v[20:21]
	v_mov_b32_e32 v20, v14
	v_mov_b32_e32 v21, v10
	v_pk_fma_f32 v[18:19], v[20:21], v[20:21], v[18:19]
	v_mov_b32_e32 v20, v15
	v_mov_b32_e32 v21, v11
	v_pk_fma_f32 v[18:19], v[20:21], v[20:21], v[18:19]
	s_nop 0
	v_add_f32_e32 v16, v16, v18
	v_add_f32_e32 v16, v16, v19
	s_nop 1
	v_add_f32_dpp v16, v16, v16 quad_perm:[1,0,3,2] row_mask:0xf bank_mask:0xf bound_ctrl:1
	s_nop 1
	v_add_f32_dpp v16, v16, v16 quad_perm:[2,3,0,1] row_mask:0xf bank_mask:0xf bound_ctrl:1
	s_nop 1
	v_add_f32_dpp v16, v16, v16 row_half_mirror row_mask:0xf bank_mask:0xf bound_ctrl:1
	s_nop 1
	v_add_f32_dpp v16, v16, v16 row_mirror row_mask:0xf bank_mask:0xf bound_ctrl:1
	s_nop 0
	v_readlane_b32 s2, v16, 16
	v_readlane_b32 s6, v16, 48
	v_readlane_b32 s0, v16, 0
	v_readlane_b32 s1, v16, 32
	v_mov_b32_e32 v16, s2
	v_mov_b32_e32 v17, s6
	v_pk_add_f32 v[16:17], s[0:1], v[16:17]
	s_mov_b32 s0, 0x800000
	v_add_f32_e32 v16, v16, v17
	v_fmamk_f32 v16, v16, 0x3a800000, v170
	v_cmp_gt_f32_e32 vcc, s0, v16
	v_mul_f32_e32 v17, 0x4b800000, v16
	s_nop 0
	v_cndmask_b32_e32 v16, v16, v17, vcc
	v_rsq_f32_e32 v16, v16
	s_nop 0
	v_mul_f32_e32 v17, 0x45800000, v16
	v_cndmask_b32_e32 v30, v16, v17, vcc
	global_load_dwordx4 v[16:19], v[86:87], off offset:48
	global_load_dwordx4 v[20:23], v[86:87], off offset:32
	global_load_dwordx4 v[24:27], v[86:87], off offset:16
	global_load_dwordx4 v[32:35], v[86:87], off
	s_waitcnt vmcnt(3)
	v_pk_mul_f32 v[16:17], v[30:31], v[16:17] op_sel_hi:[0,1]
	s_waitcnt vmcnt(2)
	v_pk_mul_f32 v[20:21], v[20:21], v[30:31] op_sel_hi:[1,0]
	s_waitcnt vmcnt(1)
	v_pk_mul_f32 v[24:25], v[24:25], v[30:31] op_sel_hi:[1,0]
	s_waitcnt vmcnt(0)
	v_pk_mul_f32 v[32:33], v[32:33], v[30:31] op_sel_hi:[1,0]
	v_pk_mul_f32 v[4:5], v[4:5], v[24:25]
	v_pk_mul_f32 v[0:1], v[0:1], v[32:33]
	v_pk_mul_f32 v[32:33], v[34:35], v[30:31] op_sel_hi:[1,0]
	v_pk_mul_f32 v[24:25], v[26:27], v[30:31] op_sel_hi:[1,0]
	v_pk_mul_f32 v[12:13], v[12:13], v[20:21]
	v_pk_mul_f32 v[20:21], v[30:31], v[22:23] op_sel_hi:[0,1]
	v_pk_mul_f32 v[8:9], v[8:9], v[16:17]
	v_pk_mul_f32 v[16:17], v[30:31], v[18:19] op_sel_hi:[0,1]
	v_pk_mul_f32 v[2:3], v[2:3], v[32:33]
	v_pk_mul_f32 v[6:7], v[6:7], v[24:25]
	v_pk_mul_f32 v[14:15], v[14:15], v[20:21]
	v_pk_mul_f32 v[10:11], v[10:11], v[16:17]
